# GEMM main loops: loop counter/pointer SALU moved ahead of the closing s_barrier (loop-edge edit), on top of the v35 stack
# baseline (speedup 1.0000x reference)
; #define PG8_STAGE(bufoff, gbase, voff) do { _Pragma("unroll") for (int _i = 0; _i < 2; ++_i) \
;         __builtin_amdgcn_global_load_lds((const unsigned*)((const char*)(gbase) + (voff)[_i]), (PG8_LAS unsigned*)(lds + (bufoff) + ldsw + _i * 8192), 16, 0, 0); } while (0)
; #define PG8_LDA(dst, b, h) do { _Pragma("unroll") for (int m = 0; m < 4; ++m) _Pragma("unroll") for (int k = 0; k < 2; ++k) dst[m][k] = *(const PG8_LAS bf16x8*)(lds + PG8_SA(b, h) + aoff + m * 2048 + k * 1024); } while (0)
; #define PG8_LDB(dst, b, h) do { _Pragma("unroll") for (int n = 0; n < 2; ++n) _Pragma("unroll") for (int k = 0; k < 2; ++k) dst[n][k] = *(const PG8_LAS bf16x8*)(lds + PG8_SB(b, h) + boff + n * 2048 + k * 1024); } while (0)
; #define PG8_MMA(ai, bj, At, Bt) do { __builtin_amdgcn_s_setprio(1); _Pragma("unroll") for (int m = 0; m < 4; ++m) _Pragma("unroll") for (int n = 0; n < 2; ++n) _Pragma("unroll") for (int k = 0; k < 2; ++k) \
;         acc[ai][bj][m][n] = __builtin_amdgcn_mfma_f32_16x16x32_bf16(Bt[n][k], At[m][k], acc[ai][bj][m][n], 0, 0, 0); __builtin_amdgcn_s_setprio(0); } while (0)
; #define PG8_WAIT_V(n) asm volatile("s_waitcnt vmcnt(" #n ")" ::: "memory")
; #define PG8_WAIT_L(n) asm volatile("s_waitcnt lgkmcnt(" #n ")" ::: "memory")
; #define PG8_BAR __builtin_amdgcn_s_barrier()
; #define PG8_SCHED __builtin_amdgcn_sched_barrier(0)
; template <class Epi, class Sched, int K, int lda, int ldb, bool ALIGN_EPI = true, bool SP2 = true>
; __device__ __forceinline__ void gemm_phase(PG8_LAS unsigned char* lds, const Sched& S, const Epi& E, const int wave_sgpr) {
;     ...
;         for (int t = 0; t < nt; t += 2) {
;             const bool last = (t == nt - 2);
;             const char* a1 = cA + (size_t)(t + 1) * kstep;
;             const char* a2 = last ? nA : cA + (size_t)(t + 2) * kstep; const char* b2 = last ? nB : cB + (size_t)(t + 2) * kstep;
;             const char* a3 = a2 + kstep; const char* b3 = b2 + kstep;
;             if constexpr (SP2) {
;             PG8_LDB(B0, 0, 0); PG8_LDB(B1, 0, 1); PG8_SCHED; PG8_LDA(At, 0, 0); PG8_STAGE(PG8_SA(1, 1), a1 + hstepA, voffA);
;             PG8_WAIT_V(8); PG8_WAIT_L(0); PG8_BAR; PG8_MMA(0, 0, At, B0); PG8_MMA(0, 1, At, B1); PG8_BAR; PG8_SCHED;
;             PG8_LDA(At, 0, 1); PG8_STAGE(PG8_SB(0, 0), b2, voffB); PG8_STAGE(PG8_SB(0, 1), b2 + hstepB, voffB); PG8_STAGE(PG8_SA(0, 0), a2, voffA);
.LBB0_190:
	s_add_u32 s20, s18, 0xfffc0080
	s_addc_u32 s21, s19, -1
	s_add_i32 s51, 0, 0x10000
	s_cmp_eq_u32 s50, 12
	s_cselect_b32 s23, s15, s21
	s_cselect_b32 s22, s14, s20
	v_add_u32_e32 v146, s51, v142
	s_cselect_b32 s21, s17, s13
	s_cselect_b32 s20, s16, s9
	s_add_i32 s53, 0, 0x14000
	ds_read_b128 v[138:141], v146
	ds_read_b128 v[148:151], v146 offset:1024
	ds_read_b128 v[152:155], v146 offset:2048
	ds_read_b128 v[158:161], v146 offset:3072
	v_add_u32_e32 v146, s53, v142
	ds_read_b128 v[162:165], v146
	ds_read_b128 v[168:171], v146 offset:1024
	ds_read_b128 v[172:175], v146 offset:2048
	ds_read_b128 v[180:183], v146 offset:3072
	v_lshl_add_u64 v[146:147], s[18:19], 0, v[136:137]
	s_add_i32 m0, s38, 0xc000
	ds_read_b128 v[184:187], v143
	ds_read_b128 v[188:191], v143 offset:1024
	ds_read_b128 v[192:195], v143 offset:2048
	ds_read_b128 v[196:199], v143 offset:3072
	ds_read_b128 v[200:203], v143 offset:4096
	ds_read_b128 v[204:207], v143 offset:5120
	ds_read_b128 v[208:211], v143 offset:6144
	ds_read_b128 v[212:215], v143 offset:7168
	global_load_lds_dwordx4 v[146:147], off
	v_lshl_add_u64 v[146:147], s[18:19], 0, v[134:135]
	s_add_i32 m0, s38, 0xe000
	s_nop 0
	global_load_lds_dwordx4 v[146:147], off
	s_waitcnt vmcnt(8)
	s_waitcnt lgkmcnt(0)
	s_barrier
	s_setprio 1
	s_waitcnt lgkmcnt(0)
	v_mfma_f32_16x16x32_bf16 v[124:127], v[138:141], v[184:187], v[124:127]
	v_mfma_f32_16x16x32_bf16 v[120:123], v[152:155], v[184:187], v[120:123]
	v_mfma_f32_16x16x32_bf16 v[116:119], v[138:141], v[192:195], v[116:119]
	v_mfma_f32_16x16x32_bf16 v[108:111], v[152:155], v[192:195], v[108:111]
	v_mfma_f32_16x16x32_bf16 v[100:103], v[138:141], v[200:203], v[100:103]
	v_mfma_f32_16x16x32_bf16 v[92:95], v[152:155], v[200:203], v[92:95]
	v_mfma_f32_16x16x32_bf16 v[84:87], v[138:141], v[208:211], v[84:87]
	v_mfma_f32_16x16x32_bf16 v[76:79], v[152:155], v[208:211], v[76:79]
	v_mfma_f32_16x16x32_bf16 v[124:127], v[148:151], v[188:191], v[124:127]
	v_mfma_f32_16x16x32_bf16 v[120:123], v[158:161], v[188:191], v[120:123]
	v_mfma_f32_16x16x32_bf16 v[116:119], v[148:151], v[196:199], v[116:119]
	v_mfma_f32_16x16x32_bf16 v[108:111], v[158:161], v[196:199], v[108:111]
	v_mfma_f32_16x16x32_bf16 v[100:103], v[148:151], v[204:207], v[100:103]
	v_mfma_f32_16x16x32_bf16 v[92:95], v[158:161], v[204:207], v[92:95]
	v_mfma_f32_16x16x32_bf16 v[84:87], v[148:151], v[212:215], v[84:87]
	v_mfma_f32_16x16x32_bf16 v[76:79], v[158:161], v[212:215], v[76:79]
	s_setprio 0
	s_setprio 1
	v_mfma_f32_16x16x32_bf16 v[112:115], v[162:165], v[184:187], v[112:115]
	v_mfma_f32_16x16x32_bf16 v[104:107], v[172:175], v[184:187], v[104:107]
	v_mfma_f32_16x16x32_bf16 v[96:99], v[162:165], v[192:195], v[96:99]
	v_mfma_f32_16x16x32_bf16 v[88:91], v[172:175], v[192:195], v[88:91]
	v_mfma_f32_16x16x32_bf16 v[80:83], v[162:165], v[200:203], v[80:83]
	v_mfma_f32_16x16x32_bf16 v[72:75], v[172:175], v[200:203], v[72:75]
	v_mfma_f32_16x16x32_bf16 v[68:71], v[162:165], v[208:211], v[68:71]
	v_mfma_f32_16x16x32_bf16 v[64:67], v[172:175], v[208:211], v[64:67]
	v_mfma_f32_16x16x32_bf16 v[112:115], v[168:171], v[188:191], v[112:115]
	v_mfma_f32_16x16x32_bf16 v[104:107], v[180:183], v[188:191], v[104:107]
	v_mfma_f32_16x16x32_bf16 v[96:99], v[168:171], v[196:199], v[96:99]
	v_mfma_f32_16x16x32_bf16 v[88:91], v[180:183], v[196:199], v[88:91]
	v_mfma_f32_16x16x32_bf16 v[80:83], v[168:171], v[204:207], v[80:83]
	v_mfma_f32_16x16x32_bf16 v[72:75], v[180:183], v[204:207], v[72:75]
	v_mfma_f32_16x16x32_bf16 v[68:71], v[168:171], v[212:215], v[68:71]
	v_mfma_f32_16x16x32_bf16 v[64:67], v[180:183], v[212:215], v[64:67]
	s_setprio 0
	s_barrier
	s_add_i32 s51, s51, s34
	v_lshl_add_u64 v[146:147], s[20:21], 0, v[144:145]
	s_mov_b32 m0, s51
	ds_read_b128 v[184:187], v143 offset:16384
	ds_read_b128 v[188:191], v143 offset:17408
	ds_read_b128 v[192:195], v143 offset:18432
	ds_read_b128 v[196:199], v143 offset:19456
	ds_read_b128 v[200:203], v143 offset:20480
	ds_read_b128 v[204:207], v143 offset:21504
	ds_read_b128 v[208:211], v143 offset:22528
	ds_read_b128 v[212:215], v143 offset:23552
	global_load_lds_dwordx4 v[146:147], off
	s_add_i32 m0, s51, 0x2000
	s_add_u32 s54, s20, 0x40000
	v_lshl_add_u64 v[176:177], s[20:21], 0, v[128:129]
	s_addc_u32 s55, s21, 0
	s_add_i32 s51, s53, s34
	global_load_lds_dwordx4 v[176:177], off
	v_lshl_add_u64 v[216:217], s[54:55], 0, v[144:145]
	s_mov_b32 m0, s51
	v_lshl_add_u64 v[218:219], s[22:23], 0, v[130:131]
	global_load_lds_dwordx4 v[216:217], off
	v_lshl_add_u64 v[216:217], s[54:55], 0, v[128:129]
	s_add_i32 m0, s51, 0x2000
	s_nop 0
	global_load_lds_dwordx4 v[216:217], off
	v_lshl_add_u64 v[216:217], s[22:23], 0, v[132:133]
	s_mov_b32 m0, s38
	s_nop 0
	global_load_lds_dwordx4 v[216:217], off
	s_mov_b32 m0, s39
	s_nop 0
	global_load_lds_dwordx4 v[218:219], off
	s_waitcnt vmcnt(8)
	s_waitcnt lgkmcnt(0)
	s_barrier
; #define PG8_STAGE(bufoff, gbase, voff) do { _Pragma("unroll") for (int _i = 0; _i < 2; ++_i) \
;         __builtin_amdgcn_global_load_lds((const unsigned*)((const char*)(gbase) + (voff)[_i]), (PG8_LAS unsigned*)(lds + (bufoff) + ldsw + _i * 8192), 16, 0, 0); } while (0)
; #define PG8_LDA(dst, b, h) do { _Pragma("unroll") for (int m = 0; m < 4; ++m) _Pragma("unroll") for (int k = 0; k < 2; ++k) dst[m][k] = *(const PG8_LAS bf16x8*)(lds + PG8_SA(b, h) + aoff + m * 2048 + k * 1024); } while (0)
; #define PG8_LDB(dst, b, h) do { _Pragma("unroll") for (int n = 0; n < 2; ++n) _Pragma("unroll") for (int k = 0; k < 2; ++k) dst[n][k] = *(const PG8_LAS bf16x8*)(lds + PG8_SB(b, h) + boff + n * 2048 + k * 1024); } while (0)
; #define PG8_MMA(ai, bj, At, Bt) do { __builtin_amdgcn_s_setprio(1); _Pragma("unroll") for (int m = 0; m < 4; ++m) _Pragma("unroll") for (int n = 0; n < 2; ++n) _Pragma("unroll") for (int k = 0; k < 2; ++k) \
;         acc[ai][bj][m][n] = __builtin_amdgcn_mfma_f32_16x16x32_bf16(Bt[n][k], At[m][k], acc[ai][bj][m][n], 0, 0, 0); __builtin_amdgcn_s_setprio(0); } while (0)
; #define PG8_WAIT_V(n) asm volatile("s_waitcnt vmcnt(" #n ")" ::: "memory")
; #define PG8_WAIT_L(n) asm volatile("s_waitcnt lgkmcnt(" #n ")" ::: "memory")
; #define PG8_BAR __builtin_amdgcn_s_barrier()
; #define PG8_SCHED __builtin_amdgcn_sched_barrier(0)
; template <class Epi, class Sched, int K, int lda, int ldb, bool ALIGN_EPI = true, bool SP2 = true>
; __device__ __forceinline__ void gemm_phase(PG8_LAS unsigned char* lds, const Sched& S, const Epi& E, const int wave_sgpr) {
;     ...
;             PG8_WAIT_V(8); PG8_WAIT_L(0); PG8_BAR; PG8_MMA(1, 0, At, B0); PG8_MMA(1, 1, At, B1); PG8_BAR; PG8_SCHED;
;             PG8_LDB(B0, 1, 0); PG8_LDB(B1, 1, 1); PG8_SCHED; PG8_LDA(At, 1, 0); PG8_STAGE(PG8_SA(0, 1), a2 + hstepA, voffA);
;             PG8_WAIT_V(8); PG8_WAIT_L(0); PG8_BAR; PG8_MMA(0, 0, At, B0); PG8_MMA(0, 1, At, B1); PG8_BAR; PG8_SCHED;
	s_setprio 1
	s_waitcnt lgkmcnt(0)
	v_mfma_f32_16x16x32_bf16 v[60:63], v[138:141], v[184:187], v[60:63]
	v_mfma_f32_16x16x32_bf16 v[56:59], v[152:155], v[184:187], v[56:59]
	v_mfma_f32_16x16x32_bf16 v[52:55], v[138:141], v[192:195], v[52:55]
	v_mfma_f32_16x16x32_bf16 v[44:47], v[152:155], v[192:195], v[44:47]
	v_mfma_f32_16x16x32_bf16 v[36:39], v[138:141], v[200:203], v[36:39]
	v_mfma_f32_16x16x32_bf16 v[28:31], v[152:155], v[200:203], v[28:31]
	v_mfma_f32_16x16x32_bf16 v[20:23], v[138:141], v[208:211], v[20:23]
	v_mfma_f32_16x16x32_bf16 v[12:15], v[152:155], v[208:211], v[12:15]
	v_mfma_f32_16x16x32_bf16 v[60:63], v[148:151], v[188:191], v[60:63]
	v_mfma_f32_16x16x32_bf16 v[56:59], v[158:161], v[188:191], v[56:59]
	v_mfma_f32_16x16x32_bf16 v[52:55], v[148:151], v[196:199], v[52:55]
	v_mfma_f32_16x16x32_bf16 v[44:47], v[158:161], v[196:199], v[44:47]
	v_mfma_f32_16x16x32_bf16 v[36:39], v[148:151], v[204:207], v[36:39]
	v_mfma_f32_16x16x32_bf16 v[28:31], v[158:161], v[204:207], v[28:31]
	v_mfma_f32_16x16x32_bf16 v[20:23], v[148:151], v[212:215], v[20:23]
	v_mfma_f32_16x16x32_bf16 v[12:15], v[158:161], v[212:215], v[12:15]
	s_setprio 0
	s_setprio 1
	v_mfma_f32_16x16x32_bf16 v[48:51], v[162:165], v[184:187], v[48:51]
	v_mfma_f32_16x16x32_bf16 v[40:43], v[172:175], v[184:187], v[40:43]
	v_mfma_f32_16x16x32_bf16 v[32:35], v[162:165], v[192:195], v[32:35]
	v_mfma_f32_16x16x32_bf16 v[24:27], v[172:175], v[192:195], v[24:27]
	v_mfma_f32_16x16x32_bf16 v[16:19], v[162:165], v[200:203], v[16:19]
	v_mfma_f32_16x16x32_bf16 v[8:11], v[172:175], v[200:203], v[8:11]
	v_mfma_f32_16x16x32_bf16 v[4:7], v[162:165], v[208:211], v[4:7]
	v_mfma_f32_16x16x32_bf16 v[0:3], v[172:175], v[208:211], v[0:3]
	v_mfma_f32_16x16x32_bf16 v[48:51], v[168:171], v[188:191], v[48:51]
	v_mfma_f32_16x16x32_bf16 v[40:43], v[180:183], v[188:191], v[40:43]
	v_mfma_f32_16x16x32_bf16 v[32:35], v[168:171], v[196:199], v[32:35]
	v_mfma_f32_16x16x32_bf16 v[24:27], v[180:183], v[196:199], v[24:27]
	v_mfma_f32_16x16x32_bf16 v[16:19], v[168:171], v[204:207], v[16:19]
	v_mfma_f32_16x16x32_bf16 v[8:11], v[180:183], v[204:207], v[8:11]
	v_mfma_f32_16x16x32_bf16 v[4:7], v[168:171], v[212:215], v[4:7]
	v_mfma_f32_16x16x32_bf16 v[0:3], v[180:183], v[212:215], v[0:3]
	s_setprio 0
	s_barrier
	s_add_i32 s51, 0, 0x18000
	v_add_u32_e32 v156, s51, v142
	s_add_i32 s53, 0, 0x1c000
	ds_read_b128 v[138:141], v156
	ds_read_b128 v[148:151], v156 offset:1024
	ds_read_b128 v[152:155], v156 offset:2048
	ds_read_b128 v[158:161], v156 offset:3072
	v_add_u32_e32 v156, s53, v142
	ds_read_b128 v[162:165], v156
	ds_read_b128 v[168:171], v156 offset:1024
	ds_read_b128 v[172:175], v156 offset:2048
	ds_read_b128 v[180:183], v156 offset:3072
	s_add_u32 s22, s22, 0x40000
	s_addc_u32 s23, s23, 0
	s_mov_b32 m0, s40
	v_lshl_add_u64 v[220:221], s[22:23], 0, v[132:133]
	ds_read_b128 v[184:187], v143 offset:32768
	ds_read_b128 v[188:191], v143 offset:33792
	ds_read_b128 v[192:195], v143 offset:34816
	ds_read_b128 v[196:199], v143 offset:35840
	ds_read_b128 v[200:203], v143 offset:36864
	ds_read_b128 v[204:207], v143 offset:37888
	ds_read_b128 v[208:211], v143 offset:38912
	ds_read_b128 v[212:215], v143 offset:39936
	global_load_lds_dwordx4 v[220:221], off
	v_lshl_add_u64 v[220:221], s[22:23], 0, v[130:131]
	s_mov_b32 m0, s41
	s_nop 0
	global_load_lds_dwordx4 v[220:221], off
	s_waitcnt vmcnt(8)
	s_waitcnt lgkmcnt(0)
	s_barrier
	s_setprio 1
	s_waitcnt lgkmcnt(0)
	v_mfma_f32_16x16x32_bf16 v[124:127], v[138:141], v[184:187], v[124:127]
	v_mfma_f32_16x16x32_bf16 v[120:123], v[152:155], v[184:187], v[120:123]
	v_mfma_f32_16x16x32_bf16 v[116:119], v[138:141], v[192:195], v[116:119]
	v_mfma_f32_16x16x32_bf16 v[108:111], v[152:155], v[192:195], v[108:111]
	v_mfma_f32_16x16x32_bf16 v[100:103], v[138:141], v[200:203], v[100:103]
	v_mfma_f32_16x16x32_bf16 v[92:95], v[152:155], v[200:203], v[92:95]
	v_mfma_f32_16x16x32_bf16 v[84:87], v[138:141], v[208:211], v[84:87]
	v_mfma_f32_16x16x32_bf16 v[76:79], v[152:155], v[208:211], v[76:79]
	v_mfma_f32_16x16x32_bf16 v[124:127], v[148:151], v[188:191], v[124:127]
	v_mfma_f32_16x16x32_bf16 v[120:123], v[158:161], v[188:191], v[120:123]
	v_mfma_f32_16x16x32_bf16 v[116:119], v[148:151], v[196:199], v[116:119]
	v_mfma_f32_16x16x32_bf16 v[108:111], v[158:161], v[196:199], v[108:111]
	v_mfma_f32_16x16x32_bf16 v[100:103], v[148:151], v[204:207], v[100:103]
	v_mfma_f32_16x16x32_bf16 v[92:95], v[158:161], v[204:207], v[92:95]
	v_mfma_f32_16x16x32_bf16 v[84:87], v[148:151], v[212:215], v[84:87]
	v_mfma_f32_16x16x32_bf16 v[76:79], v[158:161], v[212:215], v[76:79]
	s_setprio 0
	s_setprio 1
	v_mfma_f32_16x16x32_bf16 v[112:115], v[162:165], v[184:187], v[112:115]
	v_mfma_f32_16x16x32_bf16 v[104:107], v[172:175], v[184:187], v[104:107]
	v_mfma_f32_16x16x32_bf16 v[96:99], v[162:165], v[192:195], v[96:99]
	v_mfma_f32_16x16x32_bf16 v[88:91], v[172:175], v[192:195], v[88:91]
	v_mfma_f32_16x16x32_bf16 v[80:83], v[162:165], v[200:203], v[80:83]
	v_mfma_f32_16x16x32_bf16 v[72:75], v[172:175], v[200:203], v[72:75]
	v_mfma_f32_16x16x32_bf16 v[68:71], v[162:165], v[208:211], v[68:71]
	v_mfma_f32_16x16x32_bf16 v[64:67], v[172:175], v[208:211], v[64:67]
	v_mfma_f32_16x16x32_bf16 v[112:115], v[168:171], v[188:191], v[112:115]
	v_mfma_f32_16x16x32_bf16 v[104:107], v[180:183], v[188:191], v[104:107]
	v_mfma_f32_16x16x32_bf16 v[96:99], v[168:171], v[196:199], v[96:99]
	v_mfma_f32_16x16x32_bf16 v[88:91], v[180:183], v[196:199], v[88:91]
	v_mfma_f32_16x16x32_bf16 v[80:83], v[168:171], v[204:207], v[80:83]
	v_mfma_f32_16x16x32_bf16 v[72:75], v[180:183], v[204:207], v[72:75]
	v_mfma_f32_16x16x32_bf16 v[68:71], v[168:171], v[212:215], v[68:71]
	v_mfma_f32_16x16x32_bf16 v[64:67], v[180:183], v[212:215], v[64:67]
	s_setprio 0
	s_barrier
; #define PG8_STAGE(bufoff, gbase, voff) do { _Pragma("unroll") for (int _i = 0; _i < 2; ++_i) \
;         __builtin_amdgcn_global_load_lds((const unsigned*)((const char*)(gbase) + (voff)[_i]), (PG8_LAS unsigned*)(lds + (bufoff) + ldsw + _i * 8192), 16, 0, 0); } while (0)
; #define PG8_LDA(dst, b, h) do { _Pragma("unroll") for (int m = 0; m < 4; ++m) _Pragma("unroll") for (int k = 0; k < 2; ++k) dst[m][k] = *(const PG8_LAS bf16x8*)(lds + PG8_SA(b, h) + aoff + m * 2048 + k * 1024); } while (0)
; #define PG8_MMA(ai, bj, At, Bt) do { __builtin_amdgcn_s_setprio(1); _Pragma("unroll") for (int m = 0; m < 4; ++m) _Pragma("unroll") for (int n = 0; n < 2; ++n) _Pragma("unroll") for (int k = 0; k < 2; ++k) \
;         acc[ai][bj][m][n] = __builtin_amdgcn_mfma_f32_16x16x32_bf16(Bt[n][k], At[m][k], acc[ai][bj][m][n], 0, 0, 0); __builtin_amdgcn_s_setprio(0); } while (0)
; #define PG8_WAIT_V(n) asm volatile("s_waitcnt vmcnt(" #n ")" ::: "memory")
; #define PG8_WAIT_L(n) asm volatile("s_waitcnt lgkmcnt(" #n ")" ::: "memory")
; #define PG8_BAR __builtin_amdgcn_s_barrier()
; #define PG8_SCHED __builtin_amdgcn_sched_barrier(0)
; template <class Epi, class Sched, int K, int lda, int ldb, bool ALIGN_EPI = true, bool SP2 = true>
; __device__ __forceinline__ void gemm_phase(PG8_LAS unsigned char* lds, const Sched& S, const Epi& E, const int wave_sgpr) {
;     ...
;         for (int t = 0; t < nt; t += 2) {
;             const bool last = (t == nt - 2);
;     ...
;             PG8_LDA(At, 1, 1); PG8_STAGE(PG8_SB(1, 0), b3, voffB); PG8_STAGE(PG8_SB(1, 1), b3 + hstepB, voffB); PG8_STAGE(PG8_SA(1, 0), a3, voffA);
;             PG8_WAIT_V(8); PG8_WAIT_L(0); PG8_BAR; PG8_MMA(1, 0, At, B0); PG8_MMA(1, 1, At, B1); PG8_BAR; PG8_SCHED;
	s_add_i32 s22, s51, s34
	v_lshl_add_u64 v[146:147], v[146:147], 0, s[30:31]
	s_mov_b32 m0, s22
	ds_read_b128 v[184:187], v143 offset:49152
	ds_read_b128 v[188:191], v143 offset:50176
	ds_read_b128 v[192:195], v143 offset:51200
	ds_read_b128 v[196:199], v143 offset:52224
	ds_read_b128 v[200:203], v143 offset:53248
	ds_read_b128 v[204:207], v143 offset:54272
	ds_read_b128 v[208:211], v143 offset:55296
	ds_read_b128 v[212:215], v143 offset:56320
	global_load_lds_dwordx4 v[146:147], off
	s_add_i32 m0, s22, 0x2000
	s_add_u32 s20, s20, 0x40080
	v_lshl_add_u64 v[146:147], v[176:177], 0, s[30:31]
	s_addc_u32 s21, s21, 0
	s_add_i32 s22, s53, s34
	global_load_lds_dwordx4 v[146:147], off
	v_lshl_add_u64 v[146:147], s[20:21], 0, v[144:145]
	s_mov_b32 m0, s22
	s_nop 0
	global_load_lds_dwordx4 v[146:147], off
	v_lshl_add_u64 v[146:147], s[20:21], 0, v[128:129]
	s_add_i32 m0, s22, 0x2000
	s_nop 0
	global_load_lds_dwordx4 v[146:147], off
	v_lshl_add_u64 v[146:147], v[216:217], 0, s[30:31]
	s_mov_b32 m0, s44
	s_nop 0
	global_load_lds_dwordx4 v[146:147], off
	v_lshl_add_u64 v[146:147], v[218:219], 0, s[30:31]
	s_mov_b32 m0, s45
	s_nop 0
	global_load_lds_dwordx4 v[146:147], off
	s_waitcnt vmcnt(8)
	s_waitcnt lgkmcnt(0)
	s_barrier
	s_setprio 1
	s_waitcnt lgkmcnt(0)
	v_mfma_f32_16x16x32_bf16 v[60:63], v[138:141], v[184:187], v[60:63]
	v_mfma_f32_16x16x32_bf16 v[56:59], v[152:155], v[184:187], v[56:59]
	v_mfma_f32_16x16x32_bf16 v[52:55], v[138:141], v[192:195], v[52:55]
	v_mfma_f32_16x16x32_bf16 v[44:47], v[152:155], v[192:195], v[44:47]
	v_mfma_f32_16x16x32_bf16 v[36:39], v[138:141], v[200:203], v[36:39]
	v_mfma_f32_16x16x32_bf16 v[28:31], v[152:155], v[200:203], v[28:31]
	v_mfma_f32_16x16x32_bf16 v[20:23], v[138:141], v[208:211], v[20:23]
	v_mfma_f32_16x16x32_bf16 v[12:15], v[152:155], v[208:211], v[12:15]
	v_mfma_f32_16x16x32_bf16 v[60:63], v[148:151], v[188:191], v[60:63]
	v_mfma_f32_16x16x32_bf16 v[56:59], v[158:161], v[188:191], v[56:59]
	v_mfma_f32_16x16x32_bf16 v[52:55], v[148:151], v[196:199], v[52:55]
	v_mfma_f32_16x16x32_bf16 v[44:47], v[158:161], v[196:199], v[44:47]
	v_mfma_f32_16x16x32_bf16 v[36:39], v[148:151], v[204:207], v[36:39]
	v_mfma_f32_16x16x32_bf16 v[28:31], v[158:161], v[204:207], v[28:31]
	v_mfma_f32_16x16x32_bf16 v[20:23], v[148:151], v[212:215], v[20:23]
	v_mfma_f32_16x16x32_bf16 v[12:15], v[158:161], v[212:215], v[12:15]
	s_setprio 0
	s_setprio 1
	v_mfma_f32_16x16x32_bf16 v[48:51], v[162:165], v[184:187], v[48:51]
	v_mfma_f32_16x16x32_bf16 v[40:43], v[172:175], v[184:187], v[40:43]
	v_mfma_f32_16x16x32_bf16 v[32:35], v[162:165], v[192:195], v[32:35]
	v_mfma_f32_16x16x32_bf16 v[24:27], v[172:175], v[192:195], v[24:27]
	v_mfma_f32_16x16x32_bf16 v[16:19], v[162:165], v[200:203], v[16:19]
	v_mfma_f32_16x16x32_bf16 v[8:11], v[172:175], v[200:203], v[8:11]
	v_mfma_f32_16x16x32_bf16 v[4:7], v[162:165], v[208:211], v[4:7]
	v_mfma_f32_16x16x32_bf16 v[0:3], v[172:175], v[208:211], v[0:3]
	v_mfma_f32_16x16x32_bf16 v[48:51], v[168:171], v[188:191], v[48:51]
	v_mfma_f32_16x16x32_bf16 v[40:43], v[180:183], v[188:191], v[40:43]
	v_mfma_f32_16x16x32_bf16 v[32:35], v[168:171], v[196:199], v[32:35]
	v_mfma_f32_16x16x32_bf16 v[24:27], v[180:183], v[196:199], v[24:27]
	v_mfma_f32_16x16x32_bf16 v[16:19], v[168:171], v[204:207], v[16:19]
	v_mfma_f32_16x16x32_bf16 v[8:11], v[180:183], v[204:207], v[8:11]
	v_mfma_f32_16x16x32_bf16 v[4:7], v[168:171], v[212:215], v[4:7]
	v_mfma_f32_16x16x32_bf16 v[0:3], v[180:183], v[212:215], v[0:3]
	s_setprio 0
	s_add_i32 s50, s50, 2
	s_add_u32 s9, s9, 0x100
	s_addc_u32 s13, s13, 0
	s_add_u32 s18, s18, 0x100
	s_addc_u32 s19, s19, 0
	s_cmp_gt_u32 s50, 13
	s_barrier
	s_cbranch_scc0 .LBB0_190
	s_and_b64 vcc, exec, s[6:7]
	s_cbranch_vccz .LBB0_193
	s_barrier

; #define PG8_STAGE(bufoff, gbase, voff) do { _Pragma("unroll") for (int _i = 0; _i < 2; ++_i) \
;         __builtin_amdgcn_global_load_lds((const unsigned*)((const char*)(gbase) + (voff)[_i]), (PG8_LAS unsigned*)(lds + (bufoff) + ldsw + _i * 8192), 16, 0, 0); } while (0)
; #define PG8_LDA(dst, b, h) do { _Pragma("unroll") for (int m = 0; m < 4; ++m) _Pragma("unroll") for (int k = 0; k < 2; ++k) dst[m][k] = *(const PG8_LAS bf16x8*)(lds + PG8_SA(b, h) + aoff + m * 2048 + k * 1024); } while (0)
; #define PG8_LDB(dst, b, h) do { _Pragma("unroll") for (int n = 0; n < 2; ++n) _Pragma("unroll") for (int k = 0; k < 2; ++k) dst[n][k] = *(const PG8_LAS bf16x8*)(lds + PG8_SB(b, h) + boff + n * 2048 + k * 1024); } while (0)
; #define PG8_MMA(ai, bj, At, Bt) do { __builtin_amdgcn_s_setprio(1); _Pragma("unroll") for (int m = 0; m < 4; ++m) _Pragma("unroll") for (int n = 0; n < 2; ++n) _Pragma("unroll") for (int k = 0; k < 2; ++k) \
;         acc[ai][bj][m][n] = __builtin_amdgcn_mfma_f32_16x16x32_bf16(Bt[n][k], At[m][k], acc[ai][bj][m][n], 0, 0, 0); __builtin_amdgcn_s_setprio(0); } while (0)
; #define PG8_WAIT_V(n) asm volatile("s_waitcnt vmcnt(" #n ")" ::: "memory")
; #define PG8_WAIT_L(n) asm volatile("s_waitcnt lgkmcnt(" #n ")" ::: "memory")
; #define PG8_BAR __builtin_amdgcn_s_barrier()
; template <class Epi, class Sched, int K, int lda, int ldb, bool ALIGN_EPI = true, bool SP2 = true>
; __device__ __forceinline__ void gemm_phase(PG8_LAS unsigned char* lds, const Sched& S, const Epi& E, const int wave_sgpr) {
;     ...
;             const bool last = (t == nt - 2);
;             const char* a1 = cA + (size_t)(t + 1) * kstep;
;             const char* a2 = last ? nA : cA + (size_t)(t + 2) * kstep; const char* b2 = last ? nB : cB + (size_t)(t + 2) * kstep;
;             const char* a3 = a2 + kstep; const char* b3 = b2 + kstep;
;             if constexpr (SP2) {
;             PG8_LDB(B0, 0, 0); PG8_LDB(B1, 0, 1); PG8_SCHED; PG8_LDA(At, 0, 0); PG8_STAGE(PG8_SA(1, 1), a1 + hstepA, voffA);
;             PG8_WAIT_V(8); PG8_WAIT_L(0); PG8_BAR; PG8_MMA(0, 0, At, B0); PG8_MMA(0, 1, At, B1); PG8_BAR; PG8_SCHED;
;             PG8_LDA(At, 0, 1); PG8_STAGE(PG8_SB(0, 0), b2, voffB); PG8_STAGE(PG8_SB(0, 1), b2 + hstepB, voffB); PG8_STAGE(PG8_SA(0, 0), a2, voffA);
;             PG8_WAIT_V(8); PG8_WAIT_L(0); PG8_BAR; PG8_MMA(1, 0, At, B0); PG8_MMA(1, 1, At, B1); PG8_BAR; PG8_SCHED;
.LBB0_498:
	s_add_u32 s20, s18, 0xfffc0080
	s_addc_u32 s21, s19, -1
	s_add_i32 s54, 0, 0x10000
	s_cmp_eq_u32 s53, 12
	s_cselect_b32 s23, s15, s21
	s_cselect_b32 s22, s14, s20
	s_cselect_b32 s21, s17, s13
	s_cselect_b32 s20, s16, s9
	s_add_i32 s56, 0, 0x14000
	v_add_u32_e32 v60, s54, v147
	v_add_u32_e32 v146, s56, v147
	ds_read_b128 v[40:43], v60
	ds_read_b128 v[44:47], v60 offset:1024
	ds_read_b128 v[56:59], v60 offset:2048
	ds_read_b128 v[60:63], v60 offset:3072
	ds_read_b128 v[148:151], v146
	ds_read_b128 v[152:155], v146 offset:1024
	ds_read_b128 v[158:161], v146 offset:2048
	ds_read_b128 v[172:175], v146 offset:3072
	v_lshl_add_u64 v[176:177], s[18:19], 0, v[170:171]
	s_add_i32 m0, s39, 0xc000
	ds_read_b128 v[180:183], v156
	ds_read_b128 v[184:187], v156 offset:1024
	ds_read_b128 v[188:191], v156 offset:2048
	ds_read_b128 v[192:195], v156 offset:3072
	ds_read_b128 v[196:199], v156 offset:4096
	ds_read_b128 v[200:203], v156 offset:5120
	ds_read_b128 v[204:207], v156 offset:6144
	ds_read_b128 v[208:211], v156 offset:7168
	global_load_lds_dwordx4 v[176:177], off
	v_lshl_add_u64 v[176:177], s[18:19], 0, v[168:169]
	s_add_i32 m0, s39, 0xe000
	s_nop 0
	global_load_lds_dwordx4 v[176:177], off
	s_waitcnt vmcnt(8)
	s_waitcnt lgkmcnt(0)
	s_barrier
	s_setprio 1
	s_waitcnt lgkmcnt(0)
	v_mfma_f32_16x16x32_bf16 v[140:143], v[40:43], v[180:183], v[140:143]
	v_mfma_f32_16x16x32_bf16 v[136:139], v[56:59], v[180:183], v[136:139]
	v_mfma_f32_16x16x32_bf16 v[124:127], v[40:43], v[188:191], v[124:127]
	v_mfma_f32_16x16x32_bf16 v[120:123], v[56:59], v[188:191], v[120:123]
	v_mfma_f32_16x16x32_bf16 v[108:111], v[40:43], v[196:199], v[108:111]
	v_mfma_f32_16x16x32_bf16 v[104:107], v[56:59], v[196:199], v[104:107]
	v_mfma_f32_16x16x32_bf16 v[92:95], v[40:43], v[204:207], v[92:95]
	v_mfma_f32_16x16x32_bf16 v[88:91], v[56:59], v[204:207], v[88:91]
	v_mfma_f32_16x16x32_bf16 v[140:143], v[44:47], v[184:187], v[140:143]
	v_mfma_f32_16x16x32_bf16 v[136:139], v[60:63], v[184:187], v[136:139]
	v_mfma_f32_16x16x32_bf16 v[124:127], v[44:47], v[192:195], v[124:127]
	v_mfma_f32_16x16x32_bf16 v[120:123], v[60:63], v[192:195], v[120:123]
	v_mfma_f32_16x16x32_bf16 v[108:111], v[44:47], v[200:203], v[108:111]
	v_mfma_f32_16x16x32_bf16 v[104:107], v[60:63], v[200:203], v[104:107]
	v_mfma_f32_16x16x32_bf16 v[92:95], v[44:47], v[208:211], v[92:95]
	v_mfma_f32_16x16x32_bf16 v[88:91], v[60:63], v[208:211], v[88:91]
	s_setprio 0
	s_setprio 1
	v_mfma_f32_16x16x32_bf16 v[132:135], v[148:151], v[180:183], v[132:135]
	v_mfma_f32_16x16x32_bf16 v[128:131], v[158:161], v[180:183], v[128:131]
	v_mfma_f32_16x16x32_bf16 v[116:119], v[148:151], v[188:191], v[116:119]
	v_mfma_f32_16x16x32_bf16 v[112:115], v[158:161], v[188:191], v[112:115]
	v_mfma_f32_16x16x32_bf16 v[100:103], v[148:151], v[196:199], v[100:103]
	v_mfma_f32_16x16x32_bf16 v[96:99], v[158:161], v[196:199], v[96:99]
	v_mfma_f32_16x16x32_bf16 v[84:87], v[148:151], v[204:207], v[84:87]
	v_mfma_f32_16x16x32_bf16 v[80:83], v[158:161], v[204:207], v[80:83]
	v_mfma_f32_16x16x32_bf16 v[132:135], v[152:155], v[184:187], v[132:135]
	v_mfma_f32_16x16x32_bf16 v[128:131], v[172:175], v[184:187], v[128:131]
	v_mfma_f32_16x16x32_bf16 v[116:119], v[152:155], v[192:195], v[116:119]
	v_mfma_f32_16x16x32_bf16 v[112:115], v[172:175], v[192:195], v[112:115]
	v_mfma_f32_16x16x32_bf16 v[100:103], v[152:155], v[200:203], v[100:103]
	v_mfma_f32_16x16x32_bf16 v[96:99], v[172:175], v[200:203], v[96:99]
	v_mfma_f32_16x16x32_bf16 v[84:87], v[152:155], v[208:211], v[84:87]
	v_mfma_f32_16x16x32_bf16 v[80:83], v[172:175], v[208:211], v[80:83]
	s_setprio 0
	s_barrier
	s_add_i32 s54, s54, s38
	v_lshl_add_u64 v[176:177], s[20:21], 0, v[144:145]
	s_mov_b32 m0, s54
	ds_read_b128 v[180:183], v156 offset:16384
	ds_read_b128 v[184:187], v156 offset:17408
	ds_read_b128 v[188:191], v156 offset:18432
	ds_read_b128 v[192:195], v156 offset:19456
	ds_read_b128 v[196:199], v156 offset:20480
	ds_read_b128 v[200:203], v156 offset:21504
	ds_read_b128 v[204:207], v156 offset:22528
	ds_read_b128 v[208:211], v156 offset:23552
	global_load_lds_dwordx4 v[176:177], off
	s_add_i32 m0, s54, 0x2000
	s_add_u32 s54, s20, 0x40000
	v_lshl_add_u64 v[212:213], s[20:21], 0, v[162:163]
	s_addc_u32 s55, s21, 0
	s_add_i32 s56, s56, s38
	global_load_lds_dwordx4 v[212:213], off
	v_lshl_add_u64 v[214:215], s[54:55], 0, v[144:145]
	s_mov_b32 m0, s56
	v_lshl_add_u64 v[216:217], s[22:23], 0, v[164:165]
	global_load_lds_dwordx4 v[214:215], off
	v_lshl_add_u64 v[214:215], s[54:55], 0, v[162:163]
	s_add_i32 m0, s56, 0x2000
	s_nop 0
	global_load_lds_dwordx4 v[214:215], off
	v_lshl_add_u64 v[214:215], s[22:23], 0, v[166:167]
	s_mov_b32 m0, s39
	s_nop 0
	global_load_lds_dwordx4 v[214:215], off
	s_mov_b32 m0, s40
	s_nop 0
	global_load_lds_dwordx4 v[216:217], off
	s_waitcnt vmcnt(8)
	s_waitcnt lgkmcnt(0)
	s_barrier
; #define PG8_STAGE(bufoff, gbase, voff) do { _Pragma("unroll") for (int _i = 0; _i < 2; ++_i) \
;         __builtin_amdgcn_global_load_lds((const unsigned*)((const char*)(gbase) + (voff)[_i]), (PG8_LAS unsigned*)(lds + (bufoff) + ldsw + _i * 8192), 16, 0, 0); } while (0)
; #define PG8_LDA(dst, b, h) do { _Pragma("unroll") for (int m = 0; m < 4; ++m) _Pragma("unroll") for (int k = 0; k < 2; ++k) dst[m][k] = *(const PG8_LAS bf16x8*)(lds + PG8_SA(b, h) + aoff + m * 2048 + k * 1024); } while (0)
; #define PG8_LDB(dst, b, h) do { _Pragma("unroll") for (int n = 0; n < 2; ++n) _Pragma("unroll") for (int k = 0; k < 2; ++k) dst[n][k] = *(const PG8_LAS bf16x8*)(lds + PG8_SB(b, h) + boff + n * 2048 + k * 1024); } while (0)
; #define PG8_MMA(ai, bj, At, Bt) do { __builtin_amdgcn_s_setprio(1); _Pragma("unroll") for (int m = 0; m < 4; ++m) _Pragma("unroll") for (int n = 0; n < 2; ++n) _Pragma("unroll") for (int k = 0; k < 2; ++k) \
;         acc[ai][bj][m][n] = __builtin_amdgcn_mfma_f32_16x16x32_bf16(Bt[n][k], At[m][k], acc[ai][bj][m][n], 0, 0, 0); __builtin_amdgcn_s_setprio(0); } while (0)
; #define PG8_WAIT_V(n) asm volatile("s_waitcnt vmcnt(" #n ")" ::: "memory")
; #define PG8_WAIT_L(n) asm volatile("s_waitcnt lgkmcnt(" #n ")" ::: "memory")
; #define PG8_BAR __builtin_amdgcn_s_barrier()
; #define PG8_SCHED __builtin_amdgcn_sched_barrier(0)
; template <class Epi, class Sched, int K, int lda, int ldb, bool ALIGN_EPI = true, bool SP2 = true>
; __device__ __forceinline__ void gemm_phase(PG8_LAS unsigned char* lds, const Sched& S, const Epi& E, const int wave_sgpr) {
;     ...
;             PG8_WAIT_V(8); PG8_WAIT_L(0); PG8_BAR; PG8_MMA(1, 0, At, B0); PG8_MMA(1, 1, At, B1); PG8_BAR; PG8_SCHED;
;             PG8_LDB(B0, 1, 0); PG8_LDB(B1, 1, 1); PG8_SCHED; PG8_LDA(At, 1, 0); PG8_STAGE(PG8_SA(0, 1), a2 + hstepA, voffA);
;             PG8_WAIT_V(8); PG8_WAIT_L(0); PG8_BAR; PG8_MMA(0, 0, At, B0); PG8_MMA(0, 1, At, B1); PG8_BAR; PG8_SCHED;
	s_setprio 1
	s_waitcnt lgkmcnt(0)
	v_mfma_f32_16x16x32_bf16 v[76:79], v[40:43], v[180:183], v[76:79]
	v_mfma_f32_16x16x32_bf16 v[72:75], v[56:59], v[180:183], v[72:75]
	v_mfma_f32_16x16x32_bf16 v[52:55], v[40:43], v[188:191], v[52:55]
	v_mfma_f32_16x16x32_bf16 v[48:51], v[56:59], v[188:191], v[48:51]
	v_mfma_f32_16x16x32_bf16 v[28:31], v[40:43], v[196:199], v[28:31]
	v_mfma_f32_16x16x32_bf16 v[24:27], v[56:59], v[196:199], v[24:27]
	v_mfma_f32_16x16x32_bf16 v[12:15], v[40:43], v[204:207], v[12:15]
	v_mfma_f32_16x16x32_bf16 v[8:11], v[56:59], v[204:207], v[8:11]
	v_mfma_f32_16x16x32_bf16 v[76:79], v[44:47], v[184:187], v[76:79]
	v_mfma_f32_16x16x32_bf16 v[72:75], v[60:63], v[184:187], v[72:75]
	v_mfma_f32_16x16x32_bf16 v[52:55], v[44:47], v[192:195], v[52:55]
	v_mfma_f32_16x16x32_bf16 v[48:51], v[60:63], v[192:195], v[48:51]
	v_mfma_f32_16x16x32_bf16 v[28:31], v[44:47], v[200:203], v[28:31]
	v_mfma_f32_16x16x32_bf16 v[24:27], v[60:63], v[200:203], v[24:27]
	v_mfma_f32_16x16x32_bf16 v[12:15], v[44:47], v[208:211], v[12:15]
	v_mfma_f32_16x16x32_bf16 v[8:11], v[60:63], v[208:211], v[8:11]
	s_setprio 0
	s_setprio 1
	v_mfma_f32_16x16x32_bf16 v[36:39], v[148:151], v[188:191], v[36:39]
	v_mfma_f32_16x16x32_bf16 v[32:35], v[158:161], v[188:191], v[32:35]
	v_mfma_f32_16x16x32_bf16 v[20:23], v[148:151], v[196:199], v[20:23]
	v_mfma_f32_16x16x32_bf16 v[16:19], v[158:161], v[196:199], v[16:19]
	v_mfma_f32_16x16x32_bf16 v[4:7], v[148:151], v[204:207], v[4:7]
	v_mfma_f32_16x16x32_bf16 v[0:3], v[158:161], v[204:207], v[0:3]
	v_mfma_f32_16x16x32_bf16 v[40:43], v[148:151], v[180:183], v[68:71]
	v_mfma_f32_16x16x32_bf16 v[44:47], v[158:161], v[180:183], v[64:67]
	v_mfma_f32_16x16x32_bf16 v[36:39], v[152:155], v[192:195], v[36:39]
	v_mfma_f32_16x16x32_bf16 v[32:35], v[172:175], v[192:195], v[32:35]
	v_mfma_f32_16x16x32_bf16 v[20:23], v[152:155], v[200:203], v[20:23]
	v_mfma_f32_16x16x32_bf16 v[16:19], v[172:175], v[200:203], v[16:19]
	v_mfma_f32_16x16x32_bf16 v[4:7], v[152:155], v[208:211], v[4:7]
	v_mfma_f32_16x16x32_bf16 v[0:3], v[172:175], v[208:211], v[0:3]
	v_mfma_f32_16x16x32_bf16 v[40:43], v[152:155], v[184:187], v[40:43]
	v_mfma_f32_16x16x32_bf16 v[44:47], v[172:175], v[184:187], v[44:47]
	s_setprio 0
	s_barrier
	s_add_i32 s54, 0, 0x18000
	s_add_i32 s55, 0, 0x1c000
	v_add_u32_e32 v68, s54, v147
	v_add_u32_e32 v146, s55, v147
	ds_read_b128 v[56:59], v68
	ds_read_b128 v[60:63], v68 offset:1024
	ds_read_b128 v[64:67], v68 offset:2048
	ds_read_b128 v[68:71], v68 offset:3072
	ds_read_b128 v[148:151], v146
	ds_read_b128 v[152:155], v146 offset:1024
	ds_read_b128 v[158:161], v146 offset:2048
	ds_read_b128 v[172:175], v146 offset:3072
	s_add_u32 s22, s22, 0x40000
	s_addc_u32 s23, s23, 0
	s_mov_b32 m0, s41
	v_lshl_add_u64 v[218:219], s[22:23], 0, v[166:167]
	ds_read_b128 v[180:183], v156 offset:32768
	ds_read_b128 v[184:187], v156 offset:33792
	ds_read_b128 v[188:191], v156 offset:34816
	ds_read_b128 v[192:195], v156 offset:35840
	ds_read_b128 v[196:199], v156 offset:36864
	ds_read_b128 v[200:203], v156 offset:37888
	ds_read_b128 v[204:207], v156 offset:38912
	ds_read_b128 v[208:211], v156 offset:39936
	global_load_lds_dwordx4 v[218:219], off
	v_lshl_add_u64 v[218:219], s[22:23], 0, v[164:165]
	s_mov_b32 m0, s42
	s_nop 0
	global_load_lds_dwordx4 v[218:219], off
	s_waitcnt vmcnt(8)
	s_waitcnt lgkmcnt(0)
	s_barrier
	s_setprio 1
	s_waitcnt lgkmcnt(0)
	v_mfma_f32_16x16x32_bf16 v[140:143], v[56:59], v[180:183], v[140:143]
	v_mfma_f32_16x16x32_bf16 v[136:139], v[64:67], v[180:183], v[136:139]
	v_mfma_f32_16x16x32_bf16 v[124:127], v[56:59], v[188:191], v[124:127]
	v_mfma_f32_16x16x32_bf16 v[120:123], v[64:67], v[188:191], v[120:123]
	v_mfma_f32_16x16x32_bf16 v[108:111], v[56:59], v[196:199], v[108:111]
	v_mfma_f32_16x16x32_bf16 v[104:107], v[64:67], v[196:199], v[104:107]
	v_mfma_f32_16x16x32_bf16 v[92:95], v[56:59], v[204:207], v[92:95]
	v_mfma_f32_16x16x32_bf16 v[88:91], v[64:67], v[204:207], v[88:91]
	v_mfma_f32_16x16x32_bf16 v[140:143], v[60:63], v[184:187], v[140:143]
	v_mfma_f32_16x16x32_bf16 v[136:139], v[68:71], v[184:187], v[136:139]
	v_mfma_f32_16x16x32_bf16 v[124:127], v[60:63], v[192:195], v[124:127]
	v_mfma_f32_16x16x32_bf16 v[120:123], v[68:71], v[192:195], v[120:123]
	v_mfma_f32_16x16x32_bf16 v[108:111], v[60:63], v[200:203], v[108:111]
	v_mfma_f32_16x16x32_bf16 v[104:107], v[68:71], v[200:203], v[104:107]
	v_mfma_f32_16x16x32_bf16 v[92:95], v[60:63], v[208:211], v[92:95]
	v_mfma_f32_16x16x32_bf16 v[88:91], v[68:71], v[208:211], v[88:91]
	s_setprio 0
	s_setprio 1
	v_mfma_f32_16x16x32_bf16 v[132:135], v[148:151], v[180:183], v[132:135]
	v_mfma_f32_16x16x32_bf16 v[128:131], v[158:161], v[180:183], v[128:131]
	v_mfma_f32_16x16x32_bf16 v[116:119], v[148:151], v[188:191], v[116:119]
	v_mfma_f32_16x16x32_bf16 v[112:115], v[158:161], v[188:191], v[112:115]
	v_mfma_f32_16x16x32_bf16 v[100:103], v[148:151], v[196:199], v[100:103]
	v_mfma_f32_16x16x32_bf16 v[96:99], v[158:161], v[196:199], v[96:99]
	v_mfma_f32_16x16x32_bf16 v[84:87], v[148:151], v[204:207], v[84:87]
	v_mfma_f32_16x16x32_bf16 v[80:83], v[158:161], v[204:207], v[80:83]
	v_mfma_f32_16x16x32_bf16 v[132:135], v[152:155], v[184:187], v[132:135]
	v_mfma_f32_16x16x32_bf16 v[128:131], v[172:175], v[184:187], v[128:131]
	v_mfma_f32_16x16x32_bf16 v[116:119], v[152:155], v[192:195], v[116:119]
	v_mfma_f32_16x16x32_bf16 v[112:115], v[172:175], v[192:195], v[112:115]
	v_mfma_f32_16x16x32_bf16 v[100:103], v[152:155], v[200:203], v[100:103]
	v_mfma_f32_16x16x32_bf16 v[96:99], v[172:175], v[200:203], v[96:99]
	v_mfma_f32_16x16x32_bf16 v[84:87], v[152:155], v[208:211], v[84:87]
	v_mfma_f32_16x16x32_bf16 v[80:83], v[172:175], v[208:211], v[80:83]
	s_setprio 0
	s_barrier
; #define PG8_STAGE(bufoff, gbase, voff) do { _Pragma("unroll") for (int _i = 0; _i < 2; ++_i) \
;         __builtin_amdgcn_global_load_lds((const unsigned*)((const char*)(gbase) + (voff)[_i]), (PG8_LAS unsigned*)(lds + (bufoff) + ldsw + _i * 8192), 16, 0, 0); } while (0)
; #define PG8_LDA(dst, b, h) do { _Pragma("unroll") for (int m = 0; m < 4; ++m) _Pragma("unroll") for (int k = 0; k < 2; ++k) dst[m][k] = *(const PG8_LAS bf16x8*)(lds + PG8_SA(b, h) + aoff + m * 2048 + k * 1024); } while (0)
; #define PG8_MMA(ai, bj, At, Bt) do { __builtin_amdgcn_s_setprio(1); _Pragma("unroll") for (int m = 0; m < 4; ++m) _Pragma("unroll") for (int n = 0; n < 2; ++n) _Pragma("unroll") for (int k = 0; k < 2; ++k) \
;         acc[ai][bj][m][n] = __builtin_amdgcn_mfma_f32_16x16x32_bf16(Bt[n][k], At[m][k], acc[ai][bj][m][n], 0, 0, 0); __builtin_amdgcn_s_setprio(0); } while (0)
; #define PG8_WAIT_V(n) asm volatile("s_waitcnt vmcnt(" #n ")" ::: "memory")
; #define PG8_WAIT_L(n) asm volatile("s_waitcnt lgkmcnt(" #n ")" ::: "memory")
; #define PG8_BAR __builtin_amdgcn_s_barrier()
; #define PG8_SCHED __builtin_amdgcn_sched_barrier(0)
; template <class Epi, class Sched, int K, int lda, int ldb, bool ALIGN_EPI = true, bool SP2 = true>
; __device__ __forceinline__ void gemm_phase(PG8_LAS unsigned char* lds, const Sched& S, const Epi& E, const int wave_sgpr) {
;     ...
;         for (int t = 0; t < nt; t += 2) {
;     ...
;             PG8_LDA(At, 1, 1); PG8_STAGE(PG8_SB(1, 0), b3, voffB); PG8_STAGE(PG8_SB(1, 1), b3 + hstepB, voffB); PG8_STAGE(PG8_SA(1, 0), a3, voffA);
;             PG8_WAIT_V(8); PG8_WAIT_L(0); PG8_BAR; PG8_MMA(1, 0, At, B0); PG8_MMA(1, 1, At, B1); PG8_BAR; PG8_SCHED;
	s_add_i32 s22, s54, s38
	v_lshl_add_u64 v[176:177], v[176:177], 0, s[30:31]
	s_mov_b32 m0, s22
	ds_read_b128 v[180:183], v156 offset:49152
	ds_read_b128 v[184:187], v156 offset:50176
	ds_read_b128 v[188:191], v156 offset:51200
	ds_read_b128 v[192:195], v156 offset:52224
	ds_read_b128 v[196:199], v156 offset:53248
	ds_read_b128 v[200:203], v156 offset:54272
	ds_read_b128 v[204:207], v156 offset:55296
	ds_read_b128 v[208:211], v156 offset:56320
	global_load_lds_dwordx4 v[176:177], off
	s_add_i32 m0, s22, 0x2000
	s_add_u32 s20, s20, 0x40080
	v_lshl_add_u64 v[176:177], v[212:213], 0, s[30:31]
	s_addc_u32 s21, s21, 0
	s_add_i32 s22, s55, s38
	global_load_lds_dwordx4 v[176:177], off
	v_lshl_add_u64 v[176:177], s[20:21], 0, v[144:145]
	s_mov_b32 m0, s22
	s_nop 0
	global_load_lds_dwordx4 v[176:177], off
	v_lshl_add_u64 v[176:177], s[20:21], 0, v[162:163]
	s_add_i32 m0, s22, 0x2000
	s_nop 0
	global_load_lds_dwordx4 v[176:177], off
	v_lshl_add_u64 v[176:177], v[214:215], 0, s[30:31]
	s_mov_b32 m0, s48
	s_nop 0
	global_load_lds_dwordx4 v[176:177], off
	v_lshl_add_u64 v[176:177], v[216:217], 0, s[30:31]
	s_mov_b32 m0, s49
	s_nop 0
	global_load_lds_dwordx4 v[176:177], off
	s_waitcnt vmcnt(8)
	s_waitcnt lgkmcnt(0)
	s_barrier
	s_setprio 1
	s_waitcnt lgkmcnt(0)
	v_mfma_f32_16x16x32_bf16 v[76:79], v[56:59], v[180:183], v[76:79]
	v_mfma_f32_16x16x32_bf16 v[72:75], v[64:67], v[180:183], v[72:75]
	v_mfma_f32_16x16x32_bf16 v[52:55], v[56:59], v[188:191], v[52:55]
	v_mfma_f32_16x16x32_bf16 v[48:51], v[64:67], v[188:191], v[48:51]
	v_mfma_f32_16x16x32_bf16 v[28:31], v[56:59], v[196:199], v[28:31]
	v_mfma_f32_16x16x32_bf16 v[24:27], v[64:67], v[196:199], v[24:27]
	v_mfma_f32_16x16x32_bf16 v[12:15], v[56:59], v[204:207], v[12:15]
	v_mfma_f32_16x16x32_bf16 v[8:11], v[64:67], v[204:207], v[8:11]
	v_mfma_f32_16x16x32_bf16 v[76:79], v[60:63], v[184:187], v[76:79]
	v_mfma_f32_16x16x32_bf16 v[72:75], v[68:71], v[184:187], v[72:75]
	v_mfma_f32_16x16x32_bf16 v[52:55], v[60:63], v[192:195], v[52:55]
	v_mfma_f32_16x16x32_bf16 v[48:51], v[68:71], v[192:195], v[48:51]
	v_mfma_f32_16x16x32_bf16 v[28:31], v[60:63], v[200:203], v[28:31]
	v_mfma_f32_16x16x32_bf16 v[24:27], v[68:71], v[200:203], v[24:27]
	v_mfma_f32_16x16x32_bf16 v[12:15], v[60:63], v[208:211], v[12:15]
	v_mfma_f32_16x16x32_bf16 v[8:11], v[68:71], v[208:211], v[8:11]
	s_setprio 0
	s_setprio 1
	v_mfma_f32_16x16x32_bf16 v[40:43], v[148:151], v[180:183], v[40:43]
	v_mfma_f32_16x16x32_bf16 v[68:71], v[152:155], v[184:187], v[40:43]
	v_mfma_f32_16x16x32_bf16 v[40:43], v[158:161], v[180:183], v[44:47]
	v_mfma_f32_16x16x32_bf16 v[36:39], v[148:151], v[188:191], v[36:39]
	v_mfma_f32_16x16x32_bf16 v[32:35], v[158:161], v[188:191], v[32:35]
	v_mfma_f32_16x16x32_bf16 v[20:23], v[148:151], v[196:199], v[20:23]
	v_mfma_f32_16x16x32_bf16 v[16:19], v[158:161], v[196:199], v[16:19]
	v_mfma_f32_16x16x32_bf16 v[4:7], v[148:151], v[204:207], v[4:7]
	v_mfma_f32_16x16x32_bf16 v[0:3], v[158:161], v[204:207], v[0:3]
	v_mfma_f32_16x16x32_bf16 v[64:67], v[172:175], v[184:187], v[40:43]
	v_mfma_f32_16x16x32_bf16 v[36:39], v[152:155], v[192:195], v[36:39]
	v_mfma_f32_16x16x32_bf16 v[32:35], v[172:175], v[192:195], v[32:35]
	v_mfma_f32_16x16x32_bf16 v[20:23], v[152:155], v[200:203], v[20:23]
	v_mfma_f32_16x16x32_bf16 v[16:19], v[172:175], v[200:203], v[16:19]
	v_mfma_f32_16x16x32_bf16 v[4:7], v[152:155], v[208:211], v[4:7]
	v_mfma_f32_16x16x32_bf16 v[0:3], v[172:175], v[208:211], v[0:3]
	s_setprio 0
	s_add_i32 s53, s53, 2
	s_add_u32 s9, s9, 0x100
	s_addc_u32 s13, s13, 0
	s_add_u32 s18, s18, 0x100
	s_addc_u32 s19, s19, 0
	s_cmp_gt_u32 s53, 13
	s_barrier
	s_cbranch_scc0 .LBB0_498
	s_and_b64 vcc, exec, s[6:7]
	s_cbranch_vccz .LBB0_501
	s_barrier

; #define PG8_STAGE(bufoff, gbase, voff) do { _Pragma("unroll") for (int _i = 0; _i < 2; ++_i) \
;         __builtin_amdgcn_global_load_lds((const unsigned*)((const char*)(gbase) + (voff)[_i]), (PG8_LAS unsigned*)(lds + (bufoff) + ldsw + _i * 8192), 16, 0, 0); } while (0)
; #define PG8_LDA(dst, b, h) do { _Pragma("unroll") for (int m = 0; m < 4; ++m) _Pragma("unroll") for (int k = 0; k < 2; ++k) dst[m][k] = *(const PG8_LAS bf16x8*)(lds + PG8_SA(b, h) + aoff + m * 2048 + k * 1024); } while (0)
; #define PG8_LDB(dst, b, h) do { _Pragma("unroll") for (int n = 0; n < 2; ++n) _Pragma("unroll") for (int k = 0; k < 2; ++k) dst[n][k] = *(const PG8_LAS bf16x8*)(lds + PG8_SB(b, h) + boff + n * 2048 + k * 1024); } while (0)
; #define PG8_MMA(ai, bj, At, Bt) do { __builtin_amdgcn_s_setprio(1); _Pragma("unroll") for (int m = 0; m < 4; ++m) _Pragma("unroll") for (int n = 0; n < 2; ++n) _Pragma("unroll") for (int k = 0; k < 2; ++k) \
;         acc[ai][bj][m][n] = __builtin_amdgcn_mfma_f32_16x16x32_bf16(Bt[n][k], At[m][k], acc[ai][bj][m][n], 0, 0, 0); __builtin_amdgcn_s_setprio(0); } while (0)
; #define PG8_WAIT_V(n) asm volatile("s_waitcnt vmcnt(" #n ")" ::: "memory")
; #define PG8_WAIT_L(n) asm volatile("s_waitcnt lgkmcnt(" #n ")" ::: "memory")
; #define PG8_BAR __builtin_amdgcn_s_barrier()
; template <class Epi, class Sched, int K, int lda, int ldb, bool ALIGN_EPI = true, bool SP2 = true>
; __device__ __forceinline__ void gemm_phase(PG8_LAS unsigned char* lds, const Sched& S, const Epi& E, const int wave_sgpr) {
;     ...
;             const bool last = (t == nt - 2);
;             const char* a1 = cA + (size_t)(t + 1) * kstep;
;             const char* a2 = last ? nA : cA + (size_t)(t + 2) * kstep; const char* b2 = last ? nB : cB + (size_t)(t + 2) * kstep;
;             const char* a3 = a2 + kstep; const char* b3 = b2 + kstep;
;             if constexpr (SP2) {
;             PG8_LDB(B0, 0, 0); PG8_LDB(B1, 0, 1); PG8_SCHED; PG8_LDA(At, 0, 0); PG8_STAGE(PG8_SA(1, 1), a1 + hstepA, voffA);
;             PG8_WAIT_V(8); PG8_WAIT_L(0); PG8_BAR; PG8_MMA(0, 0, At, B0); PG8_MMA(0, 1, At, B1); PG8_BAR; PG8_SCHED;
;             PG8_LDA(At, 0, 1); PG8_STAGE(PG8_SB(0, 0), b2, voffB); PG8_STAGE(PG8_SB(0, 1), b2 + hstepB, voffB); PG8_STAGE(PG8_SA(0, 0), a2, voffA);
;             PG8_WAIT_V(8); PG8_WAIT_L(0); PG8_BAR; PG8_MMA(1, 0, At, B0); PG8_MMA(1, 1, At, B1); PG8_BAR; PG8_SCHED;
.LBB0_520:
	s_add_u32 s20, s18, 0xfff80080
	s_addc_u32 s21, s19, -1
	s_add_i32 s51, 0, 0x10000
	s_cmp_eq_u32 s50, 12
	s_cselect_b32 s23, s15, s21
	s_cselect_b32 s22, s14, s20
	v_add_u32_e32 v138, s51, v140
	s_cselect_b32 s21, s17, s13
	s_cselect_b32 s20, s16, s9
	s_add_i32 s53, 0, 0x14000
	ds_read_b128 v[148:151], v138
	ds_read_b128 v[152:155], v138 offset:1024
	ds_read_b128 v[158:161], v138 offset:2048
	ds_read_b128 v[162:165], v138 offset:3072
	v_add_u32_e32 v138, s53, v140
	ds_read_b128 v[166:169], v138
	ds_read_b128 v[170:173], v138 offset:1024
	ds_read_b128 v[174:177], v138 offset:2048
	ds_read_b128 v[180:183], v138 offset:3072
	v_lshl_add_u64 v[138:139], s[18:19], 0, v[136:137]
	s_add_i32 m0, s39, 0xc000
	ds_read_b128 v[184:187], v141
	ds_read_b128 v[188:191], v141 offset:1024
	ds_read_b128 v[192:195], v141 offset:2048
	ds_read_b128 v[196:199], v141 offset:3072
	ds_read_b128 v[200:203], v141 offset:4096
	ds_read_b128 v[204:207], v141 offset:5120
	ds_read_b128 v[208:211], v141 offset:6144
	ds_read_b128 v[212:215], v141 offset:7168
	global_load_lds_dwordx4 v[138:139], off
	v_lshl_add_u64 v[138:139], s[18:19], 0, v[134:135]
	s_add_i32 m0, s39, 0xe000
	s_nop 0
	global_load_lds_dwordx4 v[138:139], off
	s_waitcnt vmcnt(8)
	s_waitcnt lgkmcnt(0)
	s_barrier
	s_setprio 1
	s_waitcnt lgkmcnt(0)
	v_mfma_f32_16x16x32_bf16 v[124:127], v[148:151], v[184:187], v[124:127]
	v_mfma_f32_16x16x32_bf16 v[120:123], v[158:161], v[184:187], v[120:123]
	v_mfma_f32_16x16x32_bf16 v[116:119], v[148:151], v[192:195], v[116:119]
	v_mfma_f32_16x16x32_bf16 v[108:111], v[158:161], v[192:195], v[108:111]
	v_mfma_f32_16x16x32_bf16 v[100:103], v[148:151], v[200:203], v[100:103]
	v_mfma_f32_16x16x32_bf16 v[92:95], v[158:161], v[200:203], v[92:95]
	v_mfma_f32_16x16x32_bf16 v[84:87], v[148:151], v[208:211], v[84:87]
	v_mfma_f32_16x16x32_bf16 v[76:79], v[158:161], v[208:211], v[76:79]
	v_mfma_f32_16x16x32_bf16 v[124:127], v[152:155], v[188:191], v[124:127]
	v_mfma_f32_16x16x32_bf16 v[120:123], v[162:165], v[188:191], v[120:123]
	v_mfma_f32_16x16x32_bf16 v[116:119], v[152:155], v[196:199], v[116:119]
	v_mfma_f32_16x16x32_bf16 v[108:111], v[162:165], v[196:199], v[108:111]
	v_mfma_f32_16x16x32_bf16 v[100:103], v[152:155], v[204:207], v[100:103]
	v_mfma_f32_16x16x32_bf16 v[92:95], v[162:165], v[204:207], v[92:95]
	v_mfma_f32_16x16x32_bf16 v[84:87], v[152:155], v[212:215], v[84:87]
	v_mfma_f32_16x16x32_bf16 v[76:79], v[162:165], v[212:215], v[76:79]
	s_setprio 0
	s_setprio 1
	v_mfma_f32_16x16x32_bf16 v[112:115], v[166:169], v[184:187], v[112:115]
	v_mfma_f32_16x16x32_bf16 v[104:107], v[174:177], v[184:187], v[104:107]
	v_mfma_f32_16x16x32_bf16 v[96:99], v[166:169], v[192:195], v[96:99]
	v_mfma_f32_16x16x32_bf16 v[88:91], v[174:177], v[192:195], v[88:91]
	v_mfma_f32_16x16x32_bf16 v[80:83], v[166:169], v[200:203], v[80:83]
	v_mfma_f32_16x16x32_bf16 v[72:75], v[174:177], v[200:203], v[72:75]
	v_mfma_f32_16x16x32_bf16 v[68:71], v[166:169], v[208:211], v[68:71]
	v_mfma_f32_16x16x32_bf16 v[64:67], v[174:177], v[208:211], v[64:67]
	v_mfma_f32_16x16x32_bf16 v[112:115], v[170:173], v[188:191], v[112:115]
	v_mfma_f32_16x16x32_bf16 v[104:107], v[180:183], v[188:191], v[104:107]
	v_mfma_f32_16x16x32_bf16 v[96:99], v[170:173], v[196:199], v[96:99]
	v_mfma_f32_16x16x32_bf16 v[88:91], v[180:183], v[196:199], v[88:91]
	v_mfma_f32_16x16x32_bf16 v[80:83], v[170:173], v[204:207], v[80:83]
	v_mfma_f32_16x16x32_bf16 v[72:75], v[180:183], v[204:207], v[72:75]
	v_mfma_f32_16x16x32_bf16 v[68:71], v[170:173], v[212:215], v[68:71]
	v_mfma_f32_16x16x32_bf16 v[64:67], v[180:183], v[212:215], v[64:67]
	s_setprio 0
	s_barrier
	s_add_i32 s51, s51, s38
	v_lshl_add_u64 v[138:139], s[20:21], 0, v[144:145]
	s_mov_b32 m0, s51
	ds_read_b128 v[184:187], v141 offset:16384
	ds_read_b128 v[188:191], v141 offset:17408
	ds_read_b128 v[192:195], v141 offset:18432
	ds_read_b128 v[196:199], v141 offset:19456
	ds_read_b128 v[200:203], v141 offset:20480
	ds_read_b128 v[204:207], v141 offset:21504
	ds_read_b128 v[208:211], v141 offset:22528
	ds_read_b128 v[212:215], v141 offset:23552
	global_load_lds_dwordx4 v[138:139], off
	s_add_i32 m0, s51, 0x2000
	s_add_u32 s54, s20, 0x40000
	v_lshl_add_u64 v[142:143], s[20:21], 0, v[128:129]
	s_addc_u32 s55, s21, 0
	s_add_i32 s51, s53, s38
	global_load_lds_dwordx4 v[142:143], off
	v_lshl_add_u64 v[146:147], s[54:55], 0, v[144:145]
	s_mov_b32 m0, s51
	v_lshl_add_u64 v[216:217], s[22:23], 0, v[130:131]
	global_load_lds_dwordx4 v[146:147], off
	v_lshl_add_u64 v[146:147], s[54:55], 0, v[128:129]
	s_add_i32 m0, s51, 0x2000
	s_nop 0
	global_load_lds_dwordx4 v[146:147], off
	v_lshl_add_u64 v[146:147], s[22:23], 0, v[132:133]
	s_mov_b32 m0, s39
	s_nop 0
	global_load_lds_dwordx4 v[146:147], off
	s_mov_b32 m0, s40
	s_nop 0
	global_load_lds_dwordx4 v[216:217], off
	s_waitcnt vmcnt(8)
	s_waitcnt lgkmcnt(0)
	s_barrier
; #define PG8_STAGE(bufoff, gbase, voff) do { _Pragma("unroll") for (int _i = 0; _i < 2; ++_i) \
;         __builtin_amdgcn_global_load_lds((const unsigned*)((const char*)(gbase) + (voff)[_i]), (PG8_LAS unsigned*)(lds + (bufoff) + ldsw + _i * 8192), 16, 0, 0); } while (0)
; #define PG8_LDA(dst, b, h) do { _Pragma("unroll") for (int m = 0; m < 4; ++m) _Pragma("unroll") for (int k = 0; k < 2; ++k) dst[m][k] = *(const PG8_LAS bf16x8*)(lds + PG8_SA(b, h) + aoff + m * 2048 + k * 1024); } while (0)
; #define PG8_LDB(dst, b, h) do { _Pragma("unroll") for (int n = 0; n < 2; ++n) _Pragma("unroll") for (int k = 0; k < 2; ++k) dst[n][k] = *(const PG8_LAS bf16x8*)(lds + PG8_SB(b, h) + boff + n * 2048 + k * 1024); } while (0)
; #define PG8_MMA(ai, bj, At, Bt) do { __builtin_amdgcn_s_setprio(1); _Pragma("unroll") for (int m = 0; m < 4; ++m) _Pragma("unroll") for (int n = 0; n < 2; ++n) _Pragma("unroll") for (int k = 0; k < 2; ++k) \
;         acc[ai][bj][m][n] = __builtin_amdgcn_mfma_f32_16x16x32_bf16(Bt[n][k], At[m][k], acc[ai][bj][m][n], 0, 0, 0); __builtin_amdgcn_s_setprio(0); } while (0)
; #define PG8_WAIT_V(n) asm volatile("s_waitcnt vmcnt(" #n ")" ::: "memory")
; #define PG8_WAIT_L(n) asm volatile("s_waitcnt lgkmcnt(" #n ")" ::: "memory")
; #define PG8_BAR __builtin_amdgcn_s_barrier()
; #define PG8_SCHED __builtin_amdgcn_sched_barrier(0)
; template <class Epi, class Sched, int K, int lda, int ldb, bool ALIGN_EPI = true, bool SP2 = true>
; __device__ __forceinline__ void gemm_phase(PG8_LAS unsigned char* lds, const Sched& S, const Epi& E, const int wave_sgpr) {
;     ...
;             PG8_WAIT_V(8); PG8_WAIT_L(0); PG8_BAR; PG8_MMA(1, 0, At, B0); PG8_MMA(1, 1, At, B1); PG8_BAR; PG8_SCHED;
;             PG8_LDB(B0, 1, 0); PG8_LDB(B1, 1, 1); PG8_SCHED; PG8_LDA(At, 1, 0); PG8_STAGE(PG8_SA(0, 1), a2 + hstepA, voffA);
;             PG8_WAIT_V(8); PG8_WAIT_L(0); PG8_BAR; PG8_MMA(0, 0, At, B0); PG8_MMA(0, 1, At, B1); PG8_BAR; PG8_SCHED;
	s_setprio 1
	s_waitcnt lgkmcnt(0)
	v_mfma_f32_16x16x32_bf16 v[60:63], v[148:151], v[184:187], v[60:63]
	v_mfma_f32_16x16x32_bf16 v[56:59], v[158:161], v[184:187], v[56:59]
	v_mfma_f32_16x16x32_bf16 v[52:55], v[148:151], v[192:195], v[52:55]
	v_mfma_f32_16x16x32_bf16 v[44:47], v[158:161], v[192:195], v[44:47]
	v_mfma_f32_16x16x32_bf16 v[36:39], v[148:151], v[200:203], v[36:39]
	v_mfma_f32_16x16x32_bf16 v[28:31], v[158:161], v[200:203], v[28:31]
	v_mfma_f32_16x16x32_bf16 v[20:23], v[148:151], v[208:211], v[20:23]
	v_mfma_f32_16x16x32_bf16 v[12:15], v[158:161], v[208:211], v[12:15]
	v_mfma_f32_16x16x32_bf16 v[60:63], v[152:155], v[188:191], v[60:63]
	v_mfma_f32_16x16x32_bf16 v[56:59], v[162:165], v[188:191], v[56:59]
	v_mfma_f32_16x16x32_bf16 v[52:55], v[152:155], v[196:199], v[52:55]
	v_mfma_f32_16x16x32_bf16 v[44:47], v[162:165], v[196:199], v[44:47]
	v_mfma_f32_16x16x32_bf16 v[36:39], v[152:155], v[204:207], v[36:39]
	v_mfma_f32_16x16x32_bf16 v[28:31], v[162:165], v[204:207], v[28:31]
	v_mfma_f32_16x16x32_bf16 v[20:23], v[152:155], v[212:215], v[20:23]
	v_mfma_f32_16x16x32_bf16 v[12:15], v[162:165], v[212:215], v[12:15]
	s_setprio 0
	s_setprio 1
	v_mfma_f32_16x16x32_bf16 v[48:51], v[166:169], v[184:187], v[48:51]
	v_mfma_f32_16x16x32_bf16 v[40:43], v[174:177], v[184:187], v[40:43]
	v_mfma_f32_16x16x32_bf16 v[32:35], v[166:169], v[192:195], v[32:35]
	v_mfma_f32_16x16x32_bf16 v[24:27], v[174:177], v[192:195], v[24:27]
	v_mfma_f32_16x16x32_bf16 v[16:19], v[166:169], v[200:203], v[16:19]
	v_mfma_f32_16x16x32_bf16 v[8:11], v[174:177], v[200:203], v[8:11]
	v_mfma_f32_16x16x32_bf16 v[4:7], v[166:169], v[208:211], v[4:7]
	v_mfma_f32_16x16x32_bf16 v[0:3], v[174:177], v[208:211], v[0:3]
	v_mfma_f32_16x16x32_bf16 v[48:51], v[170:173], v[188:191], v[48:51]
	v_mfma_f32_16x16x32_bf16 v[40:43], v[180:183], v[188:191], v[40:43]
	v_mfma_f32_16x16x32_bf16 v[32:35], v[170:173], v[196:199], v[32:35]
	v_mfma_f32_16x16x32_bf16 v[24:27], v[180:183], v[196:199], v[24:27]
	v_mfma_f32_16x16x32_bf16 v[16:19], v[170:173], v[204:207], v[16:19]
	v_mfma_f32_16x16x32_bf16 v[8:11], v[180:183], v[204:207], v[8:11]
	v_mfma_f32_16x16x32_bf16 v[4:7], v[170:173], v[212:215], v[4:7]
	v_mfma_f32_16x16x32_bf16 v[0:3], v[180:183], v[212:215], v[0:3]
	s_setprio 0
	s_barrier
	s_add_i32 s51, 0, 0x18000
	v_add_u32_e32 v156, s51, v140
	s_add_i32 s53, 0, 0x1c000
	ds_read_b128 v[148:151], v156
	ds_read_b128 v[152:155], v156 offset:1024
	ds_read_b128 v[158:161], v156 offset:2048
	ds_read_b128 v[162:165], v156 offset:3072
	v_add_u32_e32 v156, s53, v140
	ds_read_b128 v[166:169], v156
	ds_read_b128 v[170:173], v156 offset:1024
	ds_read_b128 v[174:177], v156 offset:2048
	ds_read_b128 v[180:183], v156 offset:3072
	s_add_u32 s22, s22, 0x80000
	s_addc_u32 s23, s23, 0
	s_mov_b32 m0, s41
	v_lshl_add_u64 v[218:219], s[22:23], 0, v[132:133]
	ds_read_b128 v[184:187], v141 offset:32768
	ds_read_b128 v[188:191], v141 offset:33792
	ds_read_b128 v[192:195], v141 offset:34816
	ds_read_b128 v[196:199], v141 offset:35840
	ds_read_b128 v[200:203], v141 offset:36864
	ds_read_b128 v[204:207], v141 offset:37888
	ds_read_b128 v[208:211], v141 offset:38912
	ds_read_b128 v[212:215], v141 offset:39936
	global_load_lds_dwordx4 v[218:219], off
	v_lshl_add_u64 v[218:219], s[22:23], 0, v[130:131]
	s_mov_b32 m0, s42
	s_nop 0
	global_load_lds_dwordx4 v[218:219], off
	s_waitcnt vmcnt(8)
	s_waitcnt lgkmcnt(0)
	s_barrier
	s_setprio 1
	s_waitcnt lgkmcnt(0)
	v_mfma_f32_16x16x32_bf16 v[124:127], v[148:151], v[184:187], v[124:127]
	v_mfma_f32_16x16x32_bf16 v[120:123], v[158:161], v[184:187], v[120:123]
	v_mfma_f32_16x16x32_bf16 v[116:119], v[148:151], v[192:195], v[116:119]
	v_mfma_f32_16x16x32_bf16 v[108:111], v[158:161], v[192:195], v[108:111]
	v_mfma_f32_16x16x32_bf16 v[100:103], v[148:151], v[200:203], v[100:103]
	v_mfma_f32_16x16x32_bf16 v[92:95], v[158:161], v[200:203], v[92:95]
	v_mfma_f32_16x16x32_bf16 v[84:87], v[148:151], v[208:211], v[84:87]
	v_mfma_f32_16x16x32_bf16 v[76:79], v[158:161], v[208:211], v[76:79]
	v_mfma_f32_16x16x32_bf16 v[124:127], v[152:155], v[188:191], v[124:127]
	v_mfma_f32_16x16x32_bf16 v[120:123], v[162:165], v[188:191], v[120:123]
	v_mfma_f32_16x16x32_bf16 v[116:119], v[152:155], v[196:199], v[116:119]
	v_mfma_f32_16x16x32_bf16 v[108:111], v[162:165], v[196:199], v[108:111]
	v_mfma_f32_16x16x32_bf16 v[100:103], v[152:155], v[204:207], v[100:103]
	v_mfma_f32_16x16x32_bf16 v[92:95], v[162:165], v[204:207], v[92:95]
	v_mfma_f32_16x16x32_bf16 v[84:87], v[152:155], v[212:215], v[84:87]
	v_mfma_f32_16x16x32_bf16 v[76:79], v[162:165], v[212:215], v[76:79]
	s_setprio 0
	s_setprio 1
	v_mfma_f32_16x16x32_bf16 v[112:115], v[166:169], v[184:187], v[112:115]
	v_mfma_f32_16x16x32_bf16 v[104:107], v[174:177], v[184:187], v[104:107]
	v_mfma_f32_16x16x32_bf16 v[96:99], v[166:169], v[192:195], v[96:99]
	v_mfma_f32_16x16x32_bf16 v[88:91], v[174:177], v[192:195], v[88:91]
	v_mfma_f32_16x16x32_bf16 v[80:83], v[166:169], v[200:203], v[80:83]
	v_mfma_f32_16x16x32_bf16 v[72:75], v[174:177], v[200:203], v[72:75]
	v_mfma_f32_16x16x32_bf16 v[68:71], v[166:169], v[208:211], v[68:71]
	v_mfma_f32_16x16x32_bf16 v[64:67], v[174:177], v[208:211], v[64:67]
	v_mfma_f32_16x16x32_bf16 v[112:115], v[170:173], v[188:191], v[112:115]
	v_mfma_f32_16x16x32_bf16 v[104:107], v[180:183], v[188:191], v[104:107]
	v_mfma_f32_16x16x32_bf16 v[96:99], v[170:173], v[196:199], v[96:99]
	v_mfma_f32_16x16x32_bf16 v[88:91], v[180:183], v[196:199], v[88:91]
	v_mfma_f32_16x16x32_bf16 v[80:83], v[170:173], v[204:207], v[80:83]
	v_mfma_f32_16x16x32_bf16 v[72:75], v[180:183], v[204:207], v[72:75]
	v_mfma_f32_16x16x32_bf16 v[68:71], v[170:173], v[212:215], v[68:71]
	v_mfma_f32_16x16x32_bf16 v[64:67], v[180:183], v[212:215], v[64:67]
	s_setprio 0
	s_barrier
; #define PG8_STAGE(bufoff, gbase, voff) do { _Pragma("unroll") for (int _i = 0; _i < 2; ++_i) \
;         __builtin_amdgcn_global_load_lds((const unsigned*)((const char*)(gbase) + (voff)[_i]), (PG8_LAS unsigned*)(lds + (bufoff) + ldsw + _i * 8192), 16, 0, 0); } while (0)
; #define PG8_LDA(dst, b, h) do { _Pragma("unroll") for (int m = 0; m < 4; ++m) _Pragma("unroll") for (int k = 0; k < 2; ++k) dst[m][k] = *(const PG8_LAS bf16x8*)(lds + PG8_SA(b, h) + aoff + m * 2048 + k * 1024); } while (0)
; #define PG8_MMA(ai, bj, At, Bt) do { __builtin_amdgcn_s_setprio(1); _Pragma("unroll") for (int m = 0; m < 4; ++m) _Pragma("unroll") for (int n = 0; n < 2; ++n) _Pragma("unroll") for (int k = 0; k < 2; ++k) \
;         acc[ai][bj][m][n] = __builtin_amdgcn_mfma_f32_16x16x32_bf16(Bt[n][k], At[m][k], acc[ai][bj][m][n], 0, 0, 0); __builtin_amdgcn_s_setprio(0); } while (0)
; #define PG8_WAIT_V(n) asm volatile("s_waitcnt vmcnt(" #n ")" ::: "memory")
; #define PG8_WAIT_L(n) asm volatile("s_waitcnt lgkmcnt(" #n ")" ::: "memory")
; #define PG8_BAR __builtin_amdgcn_s_barrier()
; #define PG8_SCHED __builtin_amdgcn_sched_barrier(0)
; template <class Epi, class Sched, int K, int lda, int ldb, bool ALIGN_EPI = true, bool SP2 = true>
; __device__ __forceinline__ void gemm_phase(PG8_LAS unsigned char* lds, const Sched& S, const Epi& E, const int wave_sgpr) {
;     ...
;         for (int t = 0; t < nt; t += 2) {
;     ...
;             PG8_LDA(At, 1, 1); PG8_STAGE(PG8_SB(1, 0), b3, voffB); PG8_STAGE(PG8_SB(1, 1), b3 + hstepB, voffB); PG8_STAGE(PG8_SA(1, 0), a3, voffA);
;             PG8_WAIT_V(8); PG8_WAIT_L(0); PG8_BAR; PG8_MMA(1, 0, At, B0); PG8_MMA(1, 1, At, B1); PG8_BAR; PG8_SCHED;
	s_add_i32 s22, s51, s38
	v_lshl_add_u64 v[138:139], v[138:139], 0, s[30:31]
	s_mov_b32 m0, s22
	ds_read_b128 v[184:187], v141 offset:49152
	ds_read_b128 v[188:191], v141 offset:50176
	ds_read_b128 v[192:195], v141 offset:51200
	ds_read_b128 v[196:199], v141 offset:52224
	ds_read_b128 v[200:203], v141 offset:53248
	ds_read_b128 v[204:207], v141 offset:54272
	ds_read_b128 v[208:211], v141 offset:55296
	ds_read_b128 v[212:215], v141 offset:56320
	global_load_lds_dwordx4 v[138:139], off
	s_add_i32 m0, s22, 0x2000
	s_add_u32 s20, s20, 0x40080
	v_lshl_add_u64 v[138:139], v[142:143], 0, s[30:31]
	s_addc_u32 s21, s21, 0
	s_add_i32 s22, s53, s38
	global_load_lds_dwordx4 v[138:139], off
	v_lshl_add_u64 v[138:139], s[20:21], 0, v[144:145]
	s_mov_b32 m0, s22
	s_nop 0
	global_load_lds_dwordx4 v[138:139], off
	v_lshl_add_u64 v[138:139], s[20:21], 0, v[128:129]
	s_add_i32 m0, s22, 0x2000
	s_nop 0
	global_load_lds_dwordx4 v[138:139], off
	v_lshl_add_u64 v[138:139], v[146:147], 0, s[30:31]
	s_mov_b32 m0, s45
	s_nop 0
	global_load_lds_dwordx4 v[138:139], off
	v_lshl_add_u64 v[138:139], v[216:217], 0, s[30:31]
	s_mov_b32 m0, s47
	s_nop 0
	global_load_lds_dwordx4 v[138:139], off
	s_waitcnt vmcnt(8)
	s_waitcnt lgkmcnt(0)
	s_barrier
	s_setprio 1
	s_waitcnt lgkmcnt(0)
	v_mfma_f32_16x16x32_bf16 v[60:63], v[148:151], v[184:187], v[60:63]
	v_mfma_f32_16x16x32_bf16 v[56:59], v[158:161], v[184:187], v[56:59]
	v_mfma_f32_16x16x32_bf16 v[52:55], v[148:151], v[192:195], v[52:55]
	v_mfma_f32_16x16x32_bf16 v[44:47], v[158:161], v[192:195], v[44:47]
	v_mfma_f32_16x16x32_bf16 v[36:39], v[148:151], v[200:203], v[36:39]
	v_mfma_f32_16x16x32_bf16 v[28:31], v[158:161], v[200:203], v[28:31]
	v_mfma_f32_16x16x32_bf16 v[20:23], v[148:151], v[208:211], v[20:23]
	v_mfma_f32_16x16x32_bf16 v[12:15], v[158:161], v[208:211], v[12:15]
	v_mfma_f32_16x16x32_bf16 v[60:63], v[152:155], v[188:191], v[60:63]
	v_mfma_f32_16x16x32_bf16 v[56:59], v[162:165], v[188:191], v[56:59]
	v_mfma_f32_16x16x32_bf16 v[52:55], v[152:155], v[196:199], v[52:55]
	v_mfma_f32_16x16x32_bf16 v[44:47], v[162:165], v[196:199], v[44:47]
	v_mfma_f32_16x16x32_bf16 v[36:39], v[152:155], v[204:207], v[36:39]
	v_mfma_f32_16x16x32_bf16 v[28:31], v[162:165], v[204:207], v[28:31]
	v_mfma_f32_16x16x32_bf16 v[20:23], v[152:155], v[212:215], v[20:23]
	v_mfma_f32_16x16x32_bf16 v[12:15], v[162:165], v[212:215], v[12:15]
	s_setprio 0
	s_setprio 1
	v_mfma_f32_16x16x32_bf16 v[48:51], v[166:169], v[184:187], v[48:51]
	v_mfma_f32_16x16x32_bf16 v[40:43], v[174:177], v[184:187], v[40:43]
	v_mfma_f32_16x16x32_bf16 v[32:35], v[166:169], v[192:195], v[32:35]
	v_mfma_f32_16x16x32_bf16 v[24:27], v[174:177], v[192:195], v[24:27]
	v_mfma_f32_16x16x32_bf16 v[16:19], v[166:169], v[200:203], v[16:19]
	v_mfma_f32_16x16x32_bf16 v[8:11], v[174:177], v[200:203], v[8:11]
	v_mfma_f32_16x16x32_bf16 v[4:7], v[166:169], v[208:211], v[4:7]
	v_mfma_f32_16x16x32_bf16 v[0:3], v[174:177], v[208:211], v[0:3]
	v_mfma_f32_16x16x32_bf16 v[48:51], v[170:173], v[188:191], v[48:51]
	v_mfma_f32_16x16x32_bf16 v[40:43], v[180:183], v[188:191], v[40:43]
	v_mfma_f32_16x16x32_bf16 v[32:35], v[170:173], v[196:199], v[32:35]
	v_mfma_f32_16x16x32_bf16 v[24:27], v[180:183], v[196:199], v[24:27]
	v_mfma_f32_16x16x32_bf16 v[16:19], v[170:173], v[204:207], v[16:19]
	v_mfma_f32_16x16x32_bf16 v[8:11], v[180:183], v[204:207], v[8:11]
	v_mfma_f32_16x16x32_bf16 v[4:7], v[170:173], v[212:215], v[4:7]
	v_mfma_f32_16x16x32_bf16 v[0:3], v[180:183], v[212:215], v[0:3]
	s_setprio 0
	s_add_i32 s50, s50, 2
	s_add_u32 s9, s9, 0x100
	s_addc_u32 s13, s13, 0
	s_add_u32 s18, s18, 0x100
	s_addc_u32 s19, s19, 0
	s_cmp_gt_u32 s50, 13
	s_barrier
	s_cbranch_scc0 .LBB0_520
	s_and_b64 vcc, exec, s[6:7]
	s_cbranch_vccz .LBB0_523
	s_barrier

; #define PG8_STAGE(bufoff, gbase, voff) do { _Pragma("unroll") for (int _i = 0; _i < 2; ++_i) \
;         __builtin_amdgcn_global_load_lds((const unsigned*)((const char*)(gbase) + (voff)[_i]), (PG8_LAS unsigned*)(lds + (bufoff) + ldsw + _i * 8192), 16, 0, 0); } while (0)
; #define PG8_LDA(dst, b, h) do { _Pragma("unroll") for (int m = 0; m < 4; ++m) _Pragma("unroll") for (int k = 0; k < 2; ++k) dst[m][k] = *(const PG8_LAS bf16x8*)(lds + PG8_SA(b, h) + aoff + m * 2048 + k * 1024); } while (0)
; #define PG8_LDB(dst, b, h) do { _Pragma("unroll") for (int n = 0; n < 2; ++n) _Pragma("unroll") for (int k = 0; k < 2; ++k) dst[n][k] = *(const PG8_LAS bf16x8*)(lds + PG8_SB(b, h) + boff + n * 2048 + k * 1024); } while (0)
; #define PG8_MMA(ai, bj, At, Bt) do { __builtin_amdgcn_s_setprio(1); _Pragma("unroll") for (int m = 0; m < 4; ++m) _Pragma("unroll") for (int n = 0; n < 2; ++n) _Pragma("unroll") for (int k = 0; k < 2; ++k) \
;         acc[ai][bj][m][n] = __builtin_amdgcn_mfma_f32_16x16x32_bf16(Bt[n][k], At[m][k], acc[ai][bj][m][n], 0, 0, 0); __builtin_amdgcn_s_setprio(0); } while (0)
; #define PG8_WAIT_V(n) asm volatile("s_waitcnt vmcnt(" #n ")" ::: "memory")
; #define PG8_WAIT_L(n) asm volatile("s_waitcnt lgkmcnt(" #n ")" ::: "memory")
; #define PG8_BAR __builtin_amdgcn_s_barrier()
; template <class Epi, class Sched, int K, int lda, int ldb, bool ALIGN_EPI = true, bool SP2 = true>
; __device__ __forceinline__ void gemm_phase(PG8_LAS unsigned char* lds, const Sched& S, const Epi& E, const int wave_sgpr) {
;     ...
;             const bool last = (t == nt - 2);
;             const char* a1 = cA + (size_t)(t + 1) * kstep;
;             const char* a2 = last ? nA : cA + (size_t)(t + 2) * kstep; const char* b2 = last ? nB : cB + (size_t)(t + 2) * kstep;
;             const char* a3 = a2 + kstep; const char* b3 = b2 + kstep;
;             if constexpr (SP2) {
;             PG8_LDB(B0, 0, 0); PG8_LDB(B1, 0, 1); PG8_SCHED; PG8_LDA(At, 0, 0); PG8_STAGE(PG8_SA(1, 1), a1 + hstepA, voffA);
;             PG8_WAIT_V(8); PG8_WAIT_L(0); PG8_BAR; PG8_MMA(0, 0, At, B0); PG8_MMA(0, 1, At, B1); PG8_BAR; PG8_SCHED;
;             PG8_LDA(At, 0, 1); PG8_STAGE(PG8_SB(0, 0), b2, voffB); PG8_STAGE(PG8_SB(0, 1), b2 + hstepB, voffB); PG8_STAGE(PG8_SA(0, 0), a2, voffA);
;             PG8_WAIT_V(8); PG8_WAIT_L(0); PG8_BAR; PG8_MMA(1, 0, At, B0); PG8_MMA(1, 1, At, B1); PG8_BAR; PG8_SCHED;
.LBB0_1265:
	s_add_u32 s38, s36, 0xfffc0080
	s_addc_u32 s39, s37, -1
	s_add_i32 s80, 0, 0x10000
	s_cmp_eq_u32 s79, 12
	s_cselect_b32 s41, s21, s39
	s_cselect_b32 s40, s75, s38
	v_add_u32_e32 v142, s80, v147
	s_cselect_b32 s39, s76, s78
	s_cselect_b32 s38, s77, s60
	s_add_i32 s82, 0, 0x14000
	ds_read_b128 v[138:141], v142
	ds_read_b128 v[148:151], v142 offset:1024
	ds_read_b128 v[152:155], v142 offset:2048
	ds_read_b128 v[158:161], v142 offset:3072
	v_add_u32_e32 v142, s82, v147
	ds_read_b128 v[162:165], v142
	ds_read_b128 v[166:169], v142 offset:1024
	ds_read_b128 v[170:173], v142 offset:2048
	ds_read_b128 v[174:177], v142 offset:3072
	v_lshl_add_u64 v[142:143], s[36:37], 0, v[136:137]
	s_add_i32 m0, s29, 0xc000
	ds_read_b128 v[180:183], v156
	ds_read_b128 v[184:187], v156 offset:1024
	ds_read_b128 v[188:191], v156 offset:2048
	ds_read_b128 v[192:195], v156 offset:3072
	ds_read_b128 v[196:199], v156 offset:4096
	ds_read_b128 v[200:203], v156 offset:5120
	ds_read_b128 v[204:207], v156 offset:6144
	ds_read_b128 v[208:211], v156 offset:7168
	global_load_lds_dwordx4 v[142:143], off
	v_lshl_add_u64 v[142:143], s[36:37], 0, v[134:135]
	s_add_i32 m0, s29, 0xe000
	s_nop 0
	global_load_lds_dwordx4 v[142:143], off
	s_waitcnt vmcnt(8)
	s_waitcnt lgkmcnt(0)
	s_barrier
	s_setprio 1
	s_waitcnt lgkmcnt(0)
	v_mfma_f32_16x16x32_bf16 v[124:127], v[138:141], v[180:183], v[124:127]
	v_mfma_f32_16x16x32_bf16 v[120:123], v[152:155], v[180:183], v[120:123]
	v_mfma_f32_16x16x32_bf16 v[108:111], v[138:141], v[188:191], v[108:111]
	v_mfma_f32_16x16x32_bf16 v[104:107], v[152:155], v[188:191], v[104:107]
	v_mfma_f32_16x16x32_bf16 v[92:95], v[138:141], v[196:199], v[92:95]
	v_mfma_f32_16x16x32_bf16 v[88:91], v[152:155], v[196:199], v[88:91]
	v_mfma_f32_16x16x32_bf16 v[76:79], v[138:141], v[204:207], v[76:79]
	v_mfma_f32_16x16x32_bf16 v[72:75], v[152:155], v[204:207], v[72:75]
	v_mfma_f32_16x16x32_bf16 v[124:127], v[148:151], v[184:187], v[124:127]
	v_mfma_f32_16x16x32_bf16 v[120:123], v[158:161], v[184:187], v[120:123]
	v_mfma_f32_16x16x32_bf16 v[108:111], v[148:151], v[192:195], v[108:111]
	v_mfma_f32_16x16x32_bf16 v[104:107], v[158:161], v[192:195], v[104:107]
	v_mfma_f32_16x16x32_bf16 v[92:95], v[148:151], v[200:203], v[92:95]
	v_mfma_f32_16x16x32_bf16 v[88:91], v[158:161], v[200:203], v[88:91]
	v_mfma_f32_16x16x32_bf16 v[76:79], v[148:151], v[208:211], v[76:79]
	v_mfma_f32_16x16x32_bf16 v[72:75], v[158:161], v[208:211], v[72:75]
	s_setprio 0
	s_setprio 1
	v_mfma_f32_16x16x32_bf16 v[116:119], v[162:165], v[180:183], v[116:119]
	v_mfma_f32_16x16x32_bf16 v[112:115], v[170:173], v[180:183], v[112:115]
	v_mfma_f32_16x16x32_bf16 v[100:103], v[162:165], v[188:191], v[100:103]
	v_mfma_f32_16x16x32_bf16 v[96:99], v[170:173], v[188:191], v[96:99]
	v_mfma_f32_16x16x32_bf16 v[84:87], v[162:165], v[196:199], v[84:87]
	v_mfma_f32_16x16x32_bf16 v[80:83], v[170:173], v[196:199], v[80:83]
	v_mfma_f32_16x16x32_bf16 v[68:71], v[162:165], v[204:207], v[68:71]
	v_mfma_f32_16x16x32_bf16 v[64:67], v[170:173], v[204:207], v[64:67]
	v_mfma_f32_16x16x32_bf16 v[116:119], v[166:169], v[184:187], v[116:119]
	v_mfma_f32_16x16x32_bf16 v[112:115], v[174:177], v[184:187], v[112:115]
	v_mfma_f32_16x16x32_bf16 v[100:103], v[166:169], v[192:195], v[100:103]
	v_mfma_f32_16x16x32_bf16 v[96:99], v[174:177], v[192:195], v[96:99]
	v_mfma_f32_16x16x32_bf16 v[84:87], v[166:169], v[200:203], v[84:87]
	v_mfma_f32_16x16x32_bf16 v[80:83], v[174:177], v[200:203], v[80:83]
	v_mfma_f32_16x16x32_bf16 v[68:71], v[166:169], v[208:211], v[68:71]
	v_mfma_f32_16x16x32_bf16 v[64:67], v[174:177], v[208:211], v[64:67]
	s_setprio 0
	s_barrier
	s_add_i32 s80, s80, s58
	v_lshl_add_u64 v[142:143], s[38:39], 0, v[144:145]
	s_mov_b32 m0, s80
	ds_read_b128 v[180:183], v156 offset:16384
	ds_read_b128 v[184:187], v156 offset:17408
	ds_read_b128 v[188:191], v156 offset:18432
	ds_read_b128 v[192:195], v156 offset:19456
	ds_read_b128 v[196:199], v156 offset:20480
	ds_read_b128 v[200:203], v156 offset:21504
	ds_read_b128 v[204:207], v156 offset:22528
	ds_read_b128 v[208:211], v156 offset:23552
	global_load_lds_dwordx4 v[142:143], off
	s_add_i32 m0, s80, 0x2000
	s_add_u32 s80, s38, 0x40000
	v_lshl_add_u64 v[212:213], s[38:39], 0, v[132:133]
	s_addc_u32 s81, s39, 0
	s_add_i32 s82, s82, s58
	global_load_lds_dwordx4 v[212:213], off
	v_lshl_add_u64 v[214:215], s[80:81], 0, v[144:145]
	s_mov_b32 m0, s82
	v_lshl_add_u64 v[216:217], s[40:41], 0, v[130:131]
	global_load_lds_dwordx4 v[214:215], off
	v_lshl_add_u64 v[214:215], s[80:81], 0, v[132:133]
	s_add_i32 m0, s82, 0x2000
	s_nop 0
	global_load_lds_dwordx4 v[214:215], off
	v_lshl_add_u64 v[214:215], s[40:41], 0, v[128:129]
	s_mov_b32 m0, s29
	s_nop 0
	global_load_lds_dwordx4 v[214:215], off
	s_mov_b32 m0, s65
	s_nop 0
	global_load_lds_dwordx4 v[216:217], off
	s_waitcnt vmcnt(8)
	s_waitcnt lgkmcnt(0)
	s_barrier
; #define PG8_STAGE(bufoff, gbase, voff) do { _Pragma("unroll") for (int _i = 0; _i < 2; ++_i) \
;         __builtin_amdgcn_global_load_lds((const unsigned*)((const char*)(gbase) + (voff)[_i]), (PG8_LAS unsigned*)(lds + (bufoff) + ldsw + _i * 8192), 16, 0, 0); } while (0)
; #define PG8_LDA(dst, b, h) do { _Pragma("unroll") for (int m = 0; m < 4; ++m) _Pragma("unroll") for (int k = 0; k < 2; ++k) dst[m][k] = *(const PG8_LAS bf16x8*)(lds + PG8_SA(b, h) + aoff + m * 2048 + k * 1024); } while (0)
; #define PG8_LDB(dst, b, h) do { _Pragma("unroll") for (int n = 0; n < 2; ++n) _Pragma("unroll") for (int k = 0; k < 2; ++k) dst[n][k] = *(const PG8_LAS bf16x8*)(lds + PG8_SB(b, h) + boff + n * 2048 + k * 1024); } while (0)
; #define PG8_MMA(ai, bj, At, Bt) do { __builtin_amdgcn_s_setprio(1); _Pragma("unroll") for (int m = 0; m < 4; ++m) _Pragma("unroll") for (int n = 0; n < 2; ++n) _Pragma("unroll") for (int k = 0; k < 2; ++k) \
;         acc[ai][bj][m][n] = __builtin_amdgcn_mfma_f32_16x16x32_bf16(Bt[n][k], At[m][k], acc[ai][bj][m][n], 0, 0, 0); __builtin_amdgcn_s_setprio(0); } while (0)
; #define PG8_WAIT_V(n) asm volatile("s_waitcnt vmcnt(" #n ")" ::: "memory")
; #define PG8_WAIT_L(n) asm volatile("s_waitcnt lgkmcnt(" #n ")" ::: "memory")
; #define PG8_BAR __builtin_amdgcn_s_barrier()
; #define PG8_SCHED __builtin_amdgcn_sched_barrier(0)
; template <class Epi, class Sched, int K, int lda, int ldb, bool ALIGN_EPI = true, bool SP2 = true>
; __device__ __forceinline__ void gemm_phase(PG8_LAS unsigned char* lds, const Sched& S, const Epi& E, const int wave_sgpr) {
;     ...
;             PG8_WAIT_V(8); PG8_WAIT_L(0); PG8_BAR; PG8_MMA(1, 0, At, B0); PG8_MMA(1, 1, At, B1); PG8_BAR; PG8_SCHED;
;             PG8_LDB(B0, 1, 0); PG8_LDB(B1, 1, 1); PG8_SCHED; PG8_LDA(At, 1, 0); PG8_STAGE(PG8_SA(0, 1), a2 + hstepA, voffA);
;             PG8_WAIT_V(8); PG8_WAIT_L(0); PG8_BAR; PG8_MMA(0, 0, At, B0); PG8_MMA(0, 1, At, B1); PG8_BAR; PG8_SCHED;
	s_setprio 1
	s_waitcnt lgkmcnt(0)
	v_mfma_f32_16x16x32_bf16 v[60:63], v[138:141], v[180:183], v[60:63]
	v_mfma_f32_16x16x32_bf16 v[56:59], v[152:155], v[180:183], v[56:59]
	v_mfma_f32_16x16x32_bf16 v[44:47], v[138:141], v[188:191], v[44:47]
	v_mfma_f32_16x16x32_bf16 v[40:43], v[152:155], v[188:191], v[40:43]
	v_mfma_f32_16x16x32_bf16 v[28:31], v[138:141], v[196:199], v[28:31]
	v_mfma_f32_16x16x32_bf16 v[24:27], v[152:155], v[196:199], v[24:27]
	v_mfma_f32_16x16x32_bf16 v[12:15], v[138:141], v[204:207], v[12:15]
	v_mfma_f32_16x16x32_bf16 v[8:11], v[152:155], v[204:207], v[8:11]
	v_mfma_f32_16x16x32_bf16 v[60:63], v[148:151], v[184:187], v[60:63]
	v_mfma_f32_16x16x32_bf16 v[56:59], v[158:161], v[184:187], v[56:59]
	v_mfma_f32_16x16x32_bf16 v[44:47], v[148:151], v[192:195], v[44:47]
	v_mfma_f32_16x16x32_bf16 v[40:43], v[158:161], v[192:195], v[40:43]
	v_mfma_f32_16x16x32_bf16 v[28:31], v[148:151], v[200:203], v[28:31]
	v_mfma_f32_16x16x32_bf16 v[24:27], v[158:161], v[200:203], v[24:27]
	v_mfma_f32_16x16x32_bf16 v[12:15], v[148:151], v[208:211], v[12:15]
	v_mfma_f32_16x16x32_bf16 v[8:11], v[158:161], v[208:211], v[8:11]
	s_setprio 0
	s_setprio 1
	v_mfma_f32_16x16x32_bf16 v[52:55], v[162:165], v[180:183], v[52:55]
	v_mfma_f32_16x16x32_bf16 v[48:51], v[170:173], v[180:183], v[48:51]
	v_mfma_f32_16x16x32_bf16 v[36:39], v[162:165], v[188:191], v[36:39]
	v_mfma_f32_16x16x32_bf16 v[32:35], v[170:173], v[188:191], v[32:35]
	v_mfma_f32_16x16x32_bf16 v[20:23], v[162:165], v[196:199], v[20:23]
	v_mfma_f32_16x16x32_bf16 v[16:19], v[170:173], v[196:199], v[16:19]
	v_mfma_f32_16x16x32_bf16 v[4:7], v[162:165], v[204:207], v[4:7]
	v_mfma_f32_16x16x32_bf16 v[0:3], v[170:173], v[204:207], v[0:3]
	v_mfma_f32_16x16x32_bf16 v[52:55], v[166:169], v[184:187], v[52:55]
	v_mfma_f32_16x16x32_bf16 v[48:51], v[174:177], v[184:187], v[48:51]
	v_mfma_f32_16x16x32_bf16 v[36:39], v[166:169], v[192:195], v[36:39]
	v_mfma_f32_16x16x32_bf16 v[32:35], v[174:177], v[192:195], v[32:35]
	v_mfma_f32_16x16x32_bf16 v[20:23], v[166:169], v[200:203], v[20:23]
	v_mfma_f32_16x16x32_bf16 v[16:19], v[174:177], v[200:203], v[16:19]
	v_mfma_f32_16x16x32_bf16 v[4:7], v[166:169], v[208:211], v[4:7]
	v_mfma_f32_16x16x32_bf16 v[0:3], v[174:177], v[208:211], v[0:3]
	s_setprio 0
	s_barrier
	s_add_i32 s80, 0, 0x18000
	v_add_u32_e32 v146, s80, v147
	s_add_i32 s81, 0, 0x1c000
	ds_read_b128 v[138:141], v146
	ds_read_b128 v[148:151], v146 offset:1024
	ds_read_b128 v[152:155], v146 offset:2048
	ds_read_b128 v[158:161], v146 offset:3072
	v_add_u32_e32 v146, s81, v147
	ds_read_b128 v[162:165], v146
	ds_read_b128 v[166:169], v146 offset:1024
	ds_read_b128 v[170:173], v146 offset:2048
	ds_read_b128 v[174:177], v146 offset:3072
	s_add_u32 s40, s40, 0x40000
	s_addc_u32 s41, s41, 0
	s_mov_b32 m0, s66
	v_lshl_add_u64 v[218:219], s[40:41], 0, v[128:129]
	ds_read_b128 v[180:183], v156 offset:32768
	ds_read_b128 v[184:187], v156 offset:33792
	ds_read_b128 v[188:191], v156 offset:34816
	ds_read_b128 v[192:195], v156 offset:35840
	ds_read_b128 v[196:199], v156 offset:36864
	ds_read_b128 v[200:203], v156 offset:37888
	ds_read_b128 v[204:207], v156 offset:38912
	ds_read_b128 v[208:211], v156 offset:39936
	global_load_lds_dwordx4 v[218:219], off
	v_lshl_add_u64 v[218:219], s[40:41], 0, v[130:131]
	s_mov_b32 m0, s67
	s_nop 0
	global_load_lds_dwordx4 v[218:219], off
	s_waitcnt vmcnt(8)
	s_waitcnt lgkmcnt(0)
	s_barrier
	s_setprio 1
	s_waitcnt lgkmcnt(0)
	v_mfma_f32_16x16x32_bf16 v[124:127], v[138:141], v[180:183], v[124:127]
	v_mfma_f32_16x16x32_bf16 v[120:123], v[152:155], v[180:183], v[120:123]
	v_mfma_f32_16x16x32_bf16 v[108:111], v[138:141], v[188:191], v[108:111]
	v_mfma_f32_16x16x32_bf16 v[104:107], v[152:155], v[188:191], v[104:107]
	v_mfma_f32_16x16x32_bf16 v[92:95], v[138:141], v[196:199], v[92:95]
	v_mfma_f32_16x16x32_bf16 v[88:91], v[152:155], v[196:199], v[88:91]
	v_mfma_f32_16x16x32_bf16 v[76:79], v[138:141], v[204:207], v[76:79]
	v_mfma_f32_16x16x32_bf16 v[72:75], v[152:155], v[204:207], v[72:75]
	v_mfma_f32_16x16x32_bf16 v[124:127], v[148:151], v[184:187], v[124:127]
	v_mfma_f32_16x16x32_bf16 v[120:123], v[158:161], v[184:187], v[120:123]
	v_mfma_f32_16x16x32_bf16 v[108:111], v[148:151], v[192:195], v[108:111]
	v_mfma_f32_16x16x32_bf16 v[104:107], v[158:161], v[192:195], v[104:107]
	v_mfma_f32_16x16x32_bf16 v[92:95], v[148:151], v[200:203], v[92:95]
	v_mfma_f32_16x16x32_bf16 v[88:91], v[158:161], v[200:203], v[88:91]
	v_mfma_f32_16x16x32_bf16 v[76:79], v[148:151], v[208:211], v[76:79]
	v_mfma_f32_16x16x32_bf16 v[72:75], v[158:161], v[208:211], v[72:75]
	s_setprio 0
	s_setprio 1
	v_mfma_f32_16x16x32_bf16 v[116:119], v[162:165], v[180:183], v[116:119]
	v_mfma_f32_16x16x32_bf16 v[112:115], v[170:173], v[180:183], v[112:115]
	v_mfma_f32_16x16x32_bf16 v[100:103], v[162:165], v[188:191], v[100:103]
	v_mfma_f32_16x16x32_bf16 v[96:99], v[170:173], v[188:191], v[96:99]
	v_mfma_f32_16x16x32_bf16 v[84:87], v[162:165], v[196:199], v[84:87]
	v_mfma_f32_16x16x32_bf16 v[80:83], v[170:173], v[196:199], v[80:83]
	v_mfma_f32_16x16x32_bf16 v[68:71], v[162:165], v[204:207], v[68:71]
	v_mfma_f32_16x16x32_bf16 v[64:67], v[170:173], v[204:207], v[64:67]
	v_mfma_f32_16x16x32_bf16 v[116:119], v[166:169], v[184:187], v[116:119]
	v_mfma_f32_16x16x32_bf16 v[112:115], v[174:177], v[184:187], v[112:115]
	v_mfma_f32_16x16x32_bf16 v[100:103], v[166:169], v[192:195], v[100:103]
	v_mfma_f32_16x16x32_bf16 v[96:99], v[174:177], v[192:195], v[96:99]
	v_mfma_f32_16x16x32_bf16 v[84:87], v[166:169], v[200:203], v[84:87]
	v_mfma_f32_16x16x32_bf16 v[80:83], v[174:177], v[200:203], v[80:83]
	v_mfma_f32_16x16x32_bf16 v[68:71], v[166:169], v[208:211], v[68:71]
	v_mfma_f32_16x16x32_bf16 v[64:67], v[174:177], v[208:211], v[64:67]
	s_setprio 0
	s_barrier
; #define PG8_STAGE(bufoff, gbase, voff) do { _Pragma("unroll") for (int _i = 0; _i < 2; ++_i) \
;         __builtin_amdgcn_global_load_lds((const unsigned*)((const char*)(gbase) + (voff)[_i]), (PG8_LAS unsigned*)(lds + (bufoff) + ldsw + _i * 8192), 16, 0, 0); } while (0)
; #define PG8_LDA(dst, b, h) do { _Pragma("unroll") for (int m = 0; m < 4; ++m) _Pragma("unroll") for (int k = 0; k < 2; ++k) dst[m][k] = *(const PG8_LAS bf16x8*)(lds + PG8_SA(b, h) + aoff + m * 2048 + k * 1024); } while (0)
; #define PG8_MMA(ai, bj, At, Bt) do { __builtin_amdgcn_s_setprio(1); _Pragma("unroll") for (int m = 0; m < 4; ++m) _Pragma("unroll") for (int n = 0; n < 2; ++n) _Pragma("unroll") for (int k = 0; k < 2; ++k) \
;         acc[ai][bj][m][n] = __builtin_amdgcn_mfma_f32_16x16x32_bf16(Bt[n][k], At[m][k], acc[ai][bj][m][n], 0, 0, 0); __builtin_amdgcn_s_setprio(0); } while (0)
; #define PG8_WAIT_V(n) asm volatile("s_waitcnt vmcnt(" #n ")" ::: "memory")
; #define PG8_WAIT_L(n) asm volatile("s_waitcnt lgkmcnt(" #n ")" ::: "memory")
; #define PG8_BAR __builtin_amdgcn_s_barrier()
; #define PG8_SCHED __builtin_amdgcn_sched_barrier(0)
; template <class Epi, class Sched, int K, int lda, int ldb, bool ALIGN_EPI = true, bool SP2 = true>
; __device__ __forceinline__ void gemm_phase(PG8_LAS unsigned char* lds, const Sched& S, const Epi& E, const int wave_sgpr) {
;     ...
;         for (int t = 0; t < nt; t += 2) {
;     ...
;             PG8_LDA(At, 1, 1); PG8_STAGE(PG8_SB(1, 0), b3, voffB); PG8_STAGE(PG8_SB(1, 1), b3 + hstepB, voffB); PG8_STAGE(PG8_SA(1, 0), a3, voffA);
;             PG8_WAIT_V(8); PG8_WAIT_L(0); PG8_BAR; PG8_MMA(1, 0, At, B0); PG8_MMA(1, 1, At, B1); PG8_BAR; PG8_SCHED;
	s_add_i32 s40, s80, s58
	v_lshl_add_u64 v[142:143], v[142:143], 0, s[30:31]
	s_mov_b32 m0, s40
	ds_read_b128 v[180:183], v156 offset:49152
	ds_read_b128 v[184:187], v156 offset:50176
	ds_read_b128 v[188:191], v156 offset:51200
	ds_read_b128 v[192:195], v156 offset:52224
	ds_read_b128 v[196:199], v156 offset:53248
	ds_read_b128 v[200:203], v156 offset:54272
	ds_read_b128 v[204:207], v156 offset:55296
	ds_read_b128 v[208:211], v156 offset:56320
	global_load_lds_dwordx4 v[142:143], off
	s_add_i32 m0, s40, 0x2000
	s_add_u32 s38, s38, 0x40080
	v_lshl_add_u64 v[142:143], v[212:213], 0, s[30:31]
	s_addc_u32 s39, s39, 0
	s_add_i32 s40, s81, s58
	global_load_lds_dwordx4 v[142:143], off
	v_lshl_add_u64 v[142:143], s[38:39], 0, v[144:145]
	s_mov_b32 m0, s40
	s_nop 0
	global_load_lds_dwordx4 v[142:143], off
	v_lshl_add_u64 v[142:143], s[38:39], 0, v[132:133]
	s_add_i32 m0, s40, 0x2000
	s_nop 0
	global_load_lds_dwordx4 v[142:143], off
	v_lshl_add_u64 v[142:143], v[214:215], 0, s[30:31]
	s_mov_b32 m0, s70
	s_nop 0
	global_load_lds_dwordx4 v[142:143], off
	v_lshl_add_u64 v[142:143], v[216:217], 0, s[30:31]
	s_mov_b32 m0, s71
	s_nop 0
	global_load_lds_dwordx4 v[142:143], off
	s_waitcnt vmcnt(8)
	s_waitcnt lgkmcnt(0)
	s_barrier
	s_setprio 1
	s_waitcnt lgkmcnt(0)
	v_mfma_f32_16x16x32_bf16 v[60:63], v[138:141], v[180:183], v[60:63]
	v_mfma_f32_16x16x32_bf16 v[56:59], v[152:155], v[180:183], v[56:59]
	v_mfma_f32_16x16x32_bf16 v[44:47], v[138:141], v[188:191], v[44:47]
	v_mfma_f32_16x16x32_bf16 v[40:43], v[152:155], v[188:191], v[40:43]
	v_mfma_f32_16x16x32_bf16 v[28:31], v[138:141], v[196:199], v[28:31]
	v_mfma_f32_16x16x32_bf16 v[24:27], v[152:155], v[196:199], v[24:27]
	v_mfma_f32_16x16x32_bf16 v[12:15], v[138:141], v[204:207], v[12:15]
	v_mfma_f32_16x16x32_bf16 v[8:11], v[152:155], v[204:207], v[8:11]
	v_mfma_f32_16x16x32_bf16 v[60:63], v[148:151], v[184:187], v[60:63]
	v_mfma_f32_16x16x32_bf16 v[56:59], v[158:161], v[184:187], v[56:59]
	v_mfma_f32_16x16x32_bf16 v[44:47], v[148:151], v[192:195], v[44:47]
	v_mfma_f32_16x16x32_bf16 v[40:43], v[158:161], v[192:195], v[40:43]
	v_mfma_f32_16x16x32_bf16 v[28:31], v[148:151], v[200:203], v[28:31]
	v_mfma_f32_16x16x32_bf16 v[24:27], v[158:161], v[200:203], v[24:27]
	v_mfma_f32_16x16x32_bf16 v[12:15], v[148:151], v[208:211], v[12:15]
	v_mfma_f32_16x16x32_bf16 v[8:11], v[158:161], v[208:211], v[8:11]
	s_setprio 0
	s_setprio 1
	v_mfma_f32_16x16x32_bf16 v[52:55], v[162:165], v[180:183], v[52:55]
	v_mfma_f32_16x16x32_bf16 v[48:51], v[170:173], v[180:183], v[48:51]
	v_mfma_f32_16x16x32_bf16 v[36:39], v[162:165], v[188:191], v[36:39]
	v_mfma_f32_16x16x32_bf16 v[32:35], v[170:173], v[188:191], v[32:35]
	v_mfma_f32_16x16x32_bf16 v[20:23], v[162:165], v[196:199], v[20:23]
	v_mfma_f32_16x16x32_bf16 v[16:19], v[170:173], v[196:199], v[16:19]
	v_mfma_f32_16x16x32_bf16 v[4:7], v[162:165], v[204:207], v[4:7]
	v_mfma_f32_16x16x32_bf16 v[0:3], v[170:173], v[204:207], v[0:3]
	v_mfma_f32_16x16x32_bf16 v[52:55], v[166:169], v[184:187], v[52:55]
	v_mfma_f32_16x16x32_bf16 v[48:51], v[174:177], v[184:187], v[48:51]
	v_mfma_f32_16x16x32_bf16 v[36:39], v[166:169], v[192:195], v[36:39]
	v_mfma_f32_16x16x32_bf16 v[32:35], v[174:177], v[192:195], v[32:35]
	v_mfma_f32_16x16x32_bf16 v[20:23], v[166:169], v[200:203], v[20:23]
	v_mfma_f32_16x16x32_bf16 v[16:19], v[174:177], v[200:203], v[16:19]
	v_mfma_f32_16x16x32_bf16 v[4:7], v[166:169], v[208:211], v[4:7]
	v_mfma_f32_16x16x32_bf16 v[0:3], v[174:177], v[208:211], v[0:3]
	s_setprio 0
	s_add_i32 s79, s79, 2
	s_add_u32 s60, s60, 0x100
	s_addc_u32 s78, s78, 0
	s_add_u32 s36, s36, 0x100
	s_addc_u32 s37, s37, 0
	s_cmp_gt_u32 s79, 13
	s_barrier
	s_cbranch_scc0 .LBB0_1265
	s_and_b64 vcc, exec, s[18:19]
	s_cbranch_vccz .LBB0_1268
	s_barrier

; #define PG8_STAGE(bufoff, gbase, voff) do { _Pragma("unroll") for (int _i = 0; _i < 2; ++_i) \
;         __builtin_amdgcn_global_load_lds((const unsigned*)((const char*)(gbase) + (voff)[_i]), (PG8_LAS unsigned*)(lds + (bufoff) + ldsw + _i * 8192), 16, 0, 0); } while (0)
; #define PG8_LDA(dst, b, h) do { _Pragma("unroll") for (int m = 0; m < 4; ++m) _Pragma("unroll") for (int k = 0; k < 2; ++k) dst[m][k] = *(const PG8_LAS bf16x8*)(lds + PG8_SA(b, h) + aoff + m * 2048 + k * 1024); } while (0)
; #define PG8_LDB(dst, b, h) do { _Pragma("unroll") for (int n = 0; n < 2; ++n) _Pragma("unroll") for (int k = 0; k < 2; ++k) dst[n][k] = *(const PG8_LAS bf16x8*)(lds + PG8_SB(b, h) + boff + n * 2048 + k * 1024); } while (0)
; #define PG8_MMA(ai, bj, At, Bt) do { __builtin_amdgcn_s_setprio(1); _Pragma("unroll") for (int m = 0; m < 4; ++m) _Pragma("unroll") for (int n = 0; n < 2; ++n) _Pragma("unroll") for (int k = 0; k < 2; ++k) \
;         acc[ai][bj][m][n] = __builtin_amdgcn_mfma_f32_16x16x32_bf16(Bt[n][k], At[m][k], acc[ai][bj][m][n], 0, 0, 0); __builtin_amdgcn_s_setprio(0); } while (0)
; #define PG8_WAIT_V(n) asm volatile("s_waitcnt vmcnt(" #n ")" ::: "memory")
; #define PG8_WAIT_L(n) asm volatile("s_waitcnt lgkmcnt(" #n ")" ::: "memory")
; #define PG8_BAR __builtin_amdgcn_s_barrier()
; template <class Epi, class Sched, int K, int lda, int ldb, bool ALIGN_EPI = true, bool SP2 = true>
; __device__ __forceinline__ void gemm_phase(PG8_LAS unsigned char* lds, const Sched& S, const Epi& E, const int wave_sgpr) {
;     ...
;             const bool last = (t == nt - 2);
;             const char* a1 = cA + (size_t)(t + 1) * kstep;
;             const char* a2 = last ? nA : cA + (size_t)(t + 2) * kstep; const char* b2 = last ? nB : cB + (size_t)(t + 2) * kstep;
;             const char* a3 = a2 + kstep; const char* b3 = b2 + kstep;
;             if constexpr (SP2) {
;             PG8_LDB(B0, 0, 0); PG8_LDB(B1, 0, 1); PG8_SCHED; PG8_LDA(At, 0, 0); PG8_STAGE(PG8_SA(1, 1), a1 + hstepA, voffA);
;             PG8_WAIT_V(8); PG8_WAIT_L(0); PG8_BAR; PG8_MMA(0, 0, At, B0); PG8_MMA(0, 1, At, B1); PG8_BAR; PG8_SCHED;
;             PG8_LDA(At, 0, 1); PG8_STAGE(PG8_SB(0, 0), b2, voffB); PG8_STAGE(PG8_SB(0, 1), b2 + hstepB, voffB); PG8_STAGE(PG8_SA(0, 0), a2, voffA);
;             PG8_WAIT_V(8); PG8_WAIT_L(0); PG8_BAR; PG8_MMA(1, 0, At, B0); PG8_MMA(1, 1, At, B1); PG8_BAR; PG8_SCHED;
.LBB0_1366:
	s_add_u32 s18, s16, 0xfff80080
	s_addc_u32 s19, s17, -1
	s_add_i32 s51, 0, 0x10000
	s_cmp_eq_u32 s50, 28
	s_cselect_b32 s21, s9, s19
	s_cselect_b32 s20, s44, s18
	v_add_u32_e32 v142, s51, v147
	s_cselect_b32 s19, s45, s49
	s_cselect_b32 s18, s47, s48
	s_add_i32 s53, 0, 0x14000
	ds_read_b128 v[138:141], v142
	ds_read_b128 v[148:151], v142 offset:1024
	ds_read_b128 v[152:155], v142 offset:2048
	ds_read_b128 v[158:161], v142 offset:3072
	v_add_u32_e32 v142, s53, v147
	ds_read_b128 v[162:165], v142
	ds_read_b128 v[166:169], v142 offset:1024
	ds_read_b128 v[170:173], v142 offset:2048
	ds_read_b128 v[174:177], v142 offset:3072
	v_lshl_add_u64 v[142:143], s[16:17], 0, v[136:137]
	s_add_i32 m0, s27, 0xc000
	ds_read_b128 v[180:183], v156
	ds_read_b128 v[184:187], v156 offset:1024
	ds_read_b128 v[188:191], v156 offset:2048
	ds_read_b128 v[192:195], v156 offset:3072
	ds_read_b128 v[196:199], v156 offset:4096
	ds_read_b128 v[200:203], v156 offset:5120
	ds_read_b128 v[204:207], v156 offset:6144
	ds_read_b128 v[208:211], v156 offset:7168
	global_load_lds_dwordx4 v[142:143], off
	v_lshl_add_u64 v[142:143], s[16:17], 0, v[134:135]
	s_add_i32 m0, s27, 0xe000
	s_nop 0
	global_load_lds_dwordx4 v[142:143], off
	s_waitcnt vmcnt(8)
	s_waitcnt lgkmcnt(0)
	s_barrier
	s_setprio 1
	s_waitcnt lgkmcnt(0)
	v_mfma_f32_16x16x32_bf16 v[124:127], v[138:141], v[180:183], v[124:127]
	v_mfma_f32_16x16x32_bf16 v[120:123], v[152:155], v[180:183], v[120:123]
	v_mfma_f32_16x16x32_bf16 v[108:111], v[138:141], v[188:191], v[108:111]
	v_mfma_f32_16x16x32_bf16 v[104:107], v[152:155], v[188:191], v[104:107]
	v_mfma_f32_16x16x32_bf16 v[92:95], v[138:141], v[196:199], v[92:95]
	v_mfma_f32_16x16x32_bf16 v[88:91], v[152:155], v[196:199], v[88:91]
	v_mfma_f32_16x16x32_bf16 v[76:79], v[138:141], v[204:207], v[76:79]
	v_mfma_f32_16x16x32_bf16 v[72:75], v[152:155], v[204:207], v[72:75]
	v_mfma_f32_16x16x32_bf16 v[124:127], v[148:151], v[184:187], v[124:127]
	v_mfma_f32_16x16x32_bf16 v[120:123], v[158:161], v[184:187], v[120:123]
	v_mfma_f32_16x16x32_bf16 v[108:111], v[148:151], v[192:195], v[108:111]
	v_mfma_f32_16x16x32_bf16 v[104:107], v[158:161], v[192:195], v[104:107]
	v_mfma_f32_16x16x32_bf16 v[92:95], v[148:151], v[200:203], v[92:95]
	v_mfma_f32_16x16x32_bf16 v[88:91], v[158:161], v[200:203], v[88:91]
	v_mfma_f32_16x16x32_bf16 v[76:79], v[148:151], v[208:211], v[76:79]
	v_mfma_f32_16x16x32_bf16 v[72:75], v[158:161], v[208:211], v[72:75]
	s_setprio 0
	s_setprio 1
	v_mfma_f32_16x16x32_bf16 v[116:119], v[162:165], v[180:183], v[116:119]
	v_mfma_f32_16x16x32_bf16 v[112:115], v[170:173], v[180:183], v[112:115]
	v_mfma_f32_16x16x32_bf16 v[100:103], v[162:165], v[188:191], v[100:103]
	v_mfma_f32_16x16x32_bf16 v[96:99], v[170:173], v[188:191], v[96:99]
	v_mfma_f32_16x16x32_bf16 v[84:87], v[162:165], v[196:199], v[84:87]
	v_mfma_f32_16x16x32_bf16 v[80:83], v[170:173], v[196:199], v[80:83]
	v_mfma_f32_16x16x32_bf16 v[68:71], v[162:165], v[204:207], v[68:71]
	v_mfma_f32_16x16x32_bf16 v[64:67], v[170:173], v[204:207], v[64:67]
	v_mfma_f32_16x16x32_bf16 v[116:119], v[166:169], v[184:187], v[116:119]
	v_mfma_f32_16x16x32_bf16 v[112:115], v[174:177], v[184:187], v[112:115]
	v_mfma_f32_16x16x32_bf16 v[100:103], v[166:169], v[192:195], v[100:103]
	v_mfma_f32_16x16x32_bf16 v[96:99], v[174:177], v[192:195], v[96:99]
	v_mfma_f32_16x16x32_bf16 v[84:87], v[166:169], v[200:203], v[84:87]
	v_mfma_f32_16x16x32_bf16 v[80:83], v[174:177], v[200:203], v[80:83]
	v_mfma_f32_16x16x32_bf16 v[68:71], v[166:169], v[208:211], v[68:71]
	v_mfma_f32_16x16x32_bf16 v[64:67], v[174:177], v[208:211], v[64:67]
	s_setprio 0
	s_barrier
	s_add_i32 s51, s51, s26
	v_lshl_add_u64 v[142:143], s[18:19], 0, v[144:145]
	s_mov_b32 m0, s51
	ds_read_b128 v[180:183], v156 offset:16384
	ds_read_b128 v[184:187], v156 offset:17408
	ds_read_b128 v[188:191], v156 offset:18432
	ds_read_b128 v[192:195], v156 offset:19456
	ds_read_b128 v[196:199], v156 offset:20480
	ds_read_b128 v[200:203], v156 offset:21504
	ds_read_b128 v[204:207], v156 offset:22528
	ds_read_b128 v[208:211], v156 offset:23552
	global_load_lds_dwordx4 v[142:143], off
	s_add_i32 m0, s51, 0x2000
	s_add_u32 s54, s18, 0x80000
	v_lshl_add_u64 v[212:213], s[18:19], 0, v[128:129]
	s_addc_u32 s55, s19, 0
	s_add_i32 s51, s53, s26
	global_load_lds_dwordx4 v[212:213], off
	v_lshl_add_u64 v[214:215], s[54:55], 0, v[144:145]
	s_mov_b32 m0, s51
	v_lshl_add_u64 v[216:217], s[20:21], 0, v[130:131]
	global_load_lds_dwordx4 v[214:215], off
	v_lshl_add_u64 v[214:215], s[54:55], 0, v[128:129]
	s_add_i32 m0, s51, 0x2000
	s_nop 0
	global_load_lds_dwordx4 v[214:215], off
	v_lshl_add_u64 v[214:215], s[20:21], 0, v[132:133]
	s_mov_b32 m0, s27
	s_nop 0
	global_load_lds_dwordx4 v[214:215], off
	s_mov_b32 m0, s28
	s_nop 0
	global_load_lds_dwordx4 v[216:217], off
	s_waitcnt vmcnt(8)
	s_waitcnt lgkmcnt(0)
	s_barrier
; #define PG8_STAGE(bufoff, gbase, voff) do { _Pragma("unroll") for (int _i = 0; _i < 2; ++_i) \
;         __builtin_amdgcn_global_load_lds((const unsigned*)((const char*)(gbase) + (voff)[_i]), (PG8_LAS unsigned*)(lds + (bufoff) + ldsw + _i * 8192), 16, 0, 0); } while (0)
; #define PG8_LDA(dst, b, h) do { _Pragma("unroll") for (int m = 0; m < 4; ++m) _Pragma("unroll") for (int k = 0; k < 2; ++k) dst[m][k] = *(const PG8_LAS bf16x8*)(lds + PG8_SA(b, h) + aoff + m * 2048 + k * 1024); } while (0)
; #define PG8_LDB(dst, b, h) do { _Pragma("unroll") for (int n = 0; n < 2; ++n) _Pragma("unroll") for (int k = 0; k < 2; ++k) dst[n][k] = *(const PG8_LAS bf16x8*)(lds + PG8_SB(b, h) + boff + n * 2048 + k * 1024); } while (0)
; #define PG8_MMA(ai, bj, At, Bt) do { __builtin_amdgcn_s_setprio(1); _Pragma("unroll") for (int m = 0; m < 4; ++m) _Pragma("unroll") for (int n = 0; n < 2; ++n) _Pragma("unroll") for (int k = 0; k < 2; ++k) \
;         acc[ai][bj][m][n] = __builtin_amdgcn_mfma_f32_16x16x32_bf16(Bt[n][k], At[m][k], acc[ai][bj][m][n], 0, 0, 0); __builtin_amdgcn_s_setprio(0); } while (0)
; #define PG8_WAIT_V(n) asm volatile("s_waitcnt vmcnt(" #n ")" ::: "memory")
; #define PG8_WAIT_L(n) asm volatile("s_waitcnt lgkmcnt(" #n ")" ::: "memory")
; #define PG8_BAR __builtin_amdgcn_s_barrier()
; #define PG8_SCHED __builtin_amdgcn_sched_barrier(0)
; template <class Epi, class Sched, int K, int lda, int ldb, bool ALIGN_EPI = true, bool SP2 = true>
; __device__ __forceinline__ void gemm_phase(PG8_LAS unsigned char* lds, const Sched& S, const Epi& E, const int wave_sgpr) {
;     ...
;             PG8_WAIT_V(8); PG8_WAIT_L(0); PG8_BAR; PG8_MMA(1, 0, At, B0); PG8_MMA(1, 1, At, B1); PG8_BAR; PG8_SCHED;
;             PG8_LDB(B0, 1, 0); PG8_LDB(B1, 1, 1); PG8_SCHED; PG8_LDA(At, 1, 0); PG8_STAGE(PG8_SA(0, 1), a2 + hstepA, voffA);
;             PG8_WAIT_V(8); PG8_WAIT_L(0); PG8_BAR; PG8_MMA(0, 0, At, B0); PG8_MMA(0, 1, At, B1); PG8_BAR; PG8_SCHED;
	s_setprio 1
	s_waitcnt lgkmcnt(0)
	v_mfma_f32_16x16x32_bf16 v[60:63], v[138:141], v[180:183], v[60:63]
	v_mfma_f32_16x16x32_bf16 v[56:59], v[152:155], v[180:183], v[56:59]
	v_mfma_f32_16x16x32_bf16 v[44:47], v[138:141], v[188:191], v[44:47]
	v_mfma_f32_16x16x32_bf16 v[40:43], v[152:155], v[188:191], v[40:43]
	v_mfma_f32_16x16x32_bf16 v[28:31], v[138:141], v[196:199], v[28:31]
	v_mfma_f32_16x16x32_bf16 v[24:27], v[152:155], v[196:199], v[24:27]
	v_mfma_f32_16x16x32_bf16 v[12:15], v[138:141], v[204:207], v[12:15]
	v_mfma_f32_16x16x32_bf16 v[8:11], v[152:155], v[204:207], v[8:11]
	v_mfma_f32_16x16x32_bf16 v[60:63], v[148:151], v[184:187], v[60:63]
	v_mfma_f32_16x16x32_bf16 v[56:59], v[158:161], v[184:187], v[56:59]
	v_mfma_f32_16x16x32_bf16 v[44:47], v[148:151], v[192:195], v[44:47]
	v_mfma_f32_16x16x32_bf16 v[40:43], v[158:161], v[192:195], v[40:43]
	v_mfma_f32_16x16x32_bf16 v[28:31], v[148:151], v[200:203], v[28:31]
	v_mfma_f32_16x16x32_bf16 v[24:27], v[158:161], v[200:203], v[24:27]
	v_mfma_f32_16x16x32_bf16 v[12:15], v[148:151], v[208:211], v[12:15]
	v_mfma_f32_16x16x32_bf16 v[8:11], v[158:161], v[208:211], v[8:11]
	s_setprio 0
	s_setprio 1
	v_mfma_f32_16x16x32_bf16 v[52:55], v[162:165], v[180:183], v[52:55]
	v_mfma_f32_16x16x32_bf16 v[48:51], v[170:173], v[180:183], v[48:51]
	v_mfma_f32_16x16x32_bf16 v[36:39], v[162:165], v[188:191], v[36:39]
	v_mfma_f32_16x16x32_bf16 v[32:35], v[170:173], v[188:191], v[32:35]
	v_mfma_f32_16x16x32_bf16 v[20:23], v[162:165], v[196:199], v[20:23]
	v_mfma_f32_16x16x32_bf16 v[16:19], v[170:173], v[196:199], v[16:19]
	v_mfma_f32_16x16x32_bf16 v[4:7], v[162:165], v[204:207], v[4:7]
	v_mfma_f32_16x16x32_bf16 v[0:3], v[170:173], v[204:207], v[0:3]
	v_mfma_f32_16x16x32_bf16 v[52:55], v[166:169], v[184:187], v[52:55]
	v_mfma_f32_16x16x32_bf16 v[48:51], v[174:177], v[184:187], v[48:51]
	v_mfma_f32_16x16x32_bf16 v[36:39], v[166:169], v[192:195], v[36:39]
	v_mfma_f32_16x16x32_bf16 v[32:35], v[174:177], v[192:195], v[32:35]
	v_mfma_f32_16x16x32_bf16 v[20:23], v[166:169], v[200:203], v[20:23]
	v_mfma_f32_16x16x32_bf16 v[16:19], v[174:177], v[200:203], v[16:19]
	v_mfma_f32_16x16x32_bf16 v[4:7], v[166:169], v[208:211], v[4:7]
	v_mfma_f32_16x16x32_bf16 v[0:3], v[174:177], v[208:211], v[0:3]
	s_setprio 0
	s_barrier
	s_add_i32 s51, 0, 0x18000
	v_add_u32_e32 v146, s51, v147
	s_add_i32 s53, 0, 0x1c000
	ds_read_b128 v[138:141], v146
	ds_read_b128 v[148:151], v146 offset:1024
	ds_read_b128 v[152:155], v146 offset:2048
	ds_read_b128 v[158:161], v146 offset:3072
	v_add_u32_e32 v146, s53, v147
	ds_read_b128 v[162:165], v146
	ds_read_b128 v[166:169], v146 offset:1024
	ds_read_b128 v[170:173], v146 offset:2048
	ds_read_b128 v[174:177], v146 offset:3072
	s_add_u32 s20, s20, 0x80000
	s_addc_u32 s21, s21, 0
	s_mov_b32 m0, s29
	v_lshl_add_u64 v[218:219], s[20:21], 0, v[132:133]
	ds_read_b128 v[180:183], v156 offset:32768
	ds_read_b128 v[184:187], v156 offset:33792
	ds_read_b128 v[188:191], v156 offset:34816
	ds_read_b128 v[192:195], v156 offset:35840
	ds_read_b128 v[196:199], v156 offset:36864
	ds_read_b128 v[200:203], v156 offset:37888
	ds_read_b128 v[204:207], v156 offset:38912
	ds_read_b128 v[208:211], v156 offset:39936
	global_load_lds_dwordx4 v[218:219], off
	v_lshl_add_u64 v[218:219], s[20:21], 0, v[130:131]
	s_mov_b32 m0, s34
	s_nop 0
	global_load_lds_dwordx4 v[218:219], off
	s_waitcnt vmcnt(8)
	s_waitcnt lgkmcnt(0)
	s_barrier
	s_setprio 1
	s_waitcnt lgkmcnt(0)
	v_mfma_f32_16x16x32_bf16 v[124:127], v[138:141], v[180:183], v[124:127]
	v_mfma_f32_16x16x32_bf16 v[120:123], v[152:155], v[180:183], v[120:123]
	v_mfma_f32_16x16x32_bf16 v[108:111], v[138:141], v[188:191], v[108:111]
	v_mfma_f32_16x16x32_bf16 v[104:107], v[152:155], v[188:191], v[104:107]
	v_mfma_f32_16x16x32_bf16 v[92:95], v[138:141], v[196:199], v[92:95]
	v_mfma_f32_16x16x32_bf16 v[88:91], v[152:155], v[196:199], v[88:91]
	v_mfma_f32_16x16x32_bf16 v[76:79], v[138:141], v[204:207], v[76:79]
	v_mfma_f32_16x16x32_bf16 v[72:75], v[152:155], v[204:207], v[72:75]
	v_mfma_f32_16x16x32_bf16 v[124:127], v[148:151], v[184:187], v[124:127]
	v_mfma_f32_16x16x32_bf16 v[120:123], v[158:161], v[184:187], v[120:123]
	v_mfma_f32_16x16x32_bf16 v[108:111], v[148:151], v[192:195], v[108:111]
	v_mfma_f32_16x16x32_bf16 v[104:107], v[158:161], v[192:195], v[104:107]
	v_mfma_f32_16x16x32_bf16 v[92:95], v[148:151], v[200:203], v[92:95]
	v_mfma_f32_16x16x32_bf16 v[88:91], v[158:161], v[200:203], v[88:91]
	v_mfma_f32_16x16x32_bf16 v[76:79], v[148:151], v[208:211], v[76:79]
	v_mfma_f32_16x16x32_bf16 v[72:75], v[158:161], v[208:211], v[72:75]
	s_setprio 0
	s_setprio 1
	v_mfma_f32_16x16x32_bf16 v[116:119], v[162:165], v[180:183], v[116:119]
	v_mfma_f32_16x16x32_bf16 v[112:115], v[170:173], v[180:183], v[112:115]
	v_mfma_f32_16x16x32_bf16 v[100:103], v[162:165], v[188:191], v[100:103]
	v_mfma_f32_16x16x32_bf16 v[96:99], v[170:173], v[188:191], v[96:99]
	v_mfma_f32_16x16x32_bf16 v[84:87], v[162:165], v[196:199], v[84:87]
	v_mfma_f32_16x16x32_bf16 v[80:83], v[170:173], v[196:199], v[80:83]
	v_mfma_f32_16x16x32_bf16 v[68:71], v[162:165], v[204:207], v[68:71]
	v_mfma_f32_16x16x32_bf16 v[64:67], v[170:173], v[204:207], v[64:67]
	v_mfma_f32_16x16x32_bf16 v[116:119], v[166:169], v[184:187], v[116:119]
	v_mfma_f32_16x16x32_bf16 v[112:115], v[174:177], v[184:187], v[112:115]
	v_mfma_f32_16x16x32_bf16 v[100:103], v[166:169], v[192:195], v[100:103]
	v_mfma_f32_16x16x32_bf16 v[96:99], v[174:177], v[192:195], v[96:99]
	v_mfma_f32_16x16x32_bf16 v[84:87], v[166:169], v[200:203], v[84:87]
	v_mfma_f32_16x16x32_bf16 v[80:83], v[174:177], v[200:203], v[80:83]
	v_mfma_f32_16x16x32_bf16 v[68:71], v[166:169], v[208:211], v[68:71]
	v_mfma_f32_16x16x32_bf16 v[64:67], v[174:177], v[208:211], v[64:67]
	s_setprio 0
	s_barrier
; #define PG8_STAGE(bufoff, gbase, voff) do { _Pragma("unroll") for (int _i = 0; _i < 2; ++_i) \
;         __builtin_amdgcn_global_load_lds((const unsigned*)((const char*)(gbase) + (voff)[_i]), (PG8_LAS unsigned*)(lds + (bufoff) + ldsw + _i * 8192), 16, 0, 0); } while (0)
; #define PG8_LDA(dst, b, h) do { _Pragma("unroll") for (int m = 0; m < 4; ++m) _Pragma("unroll") for (int k = 0; k < 2; ++k) dst[m][k] = *(const PG8_LAS bf16x8*)(lds + PG8_SA(b, h) + aoff + m * 2048 + k * 1024); } while (0)
; #define PG8_MMA(ai, bj, At, Bt) do { __builtin_amdgcn_s_setprio(1); _Pragma("unroll") for (int m = 0; m < 4; ++m) _Pragma("unroll") for (int n = 0; n < 2; ++n) _Pragma("unroll") for (int k = 0; k < 2; ++k) \
;         acc[ai][bj][m][n] = __builtin_amdgcn_mfma_f32_16x16x32_bf16(Bt[n][k], At[m][k], acc[ai][bj][m][n], 0, 0, 0); __builtin_amdgcn_s_setprio(0); } while (0)
; #define PG8_WAIT_V(n) asm volatile("s_waitcnt vmcnt(" #n ")" ::: "memory")
; #define PG8_WAIT_L(n) asm volatile("s_waitcnt lgkmcnt(" #n ")" ::: "memory")
; #define PG8_BAR __builtin_amdgcn_s_barrier()
; #define PG8_SCHED __builtin_amdgcn_sched_barrier(0)
; template <class Epi, class Sched, int K, int lda, int ldb, bool ALIGN_EPI = true, bool SP2 = true>
; __device__ __forceinline__ void gemm_phase(PG8_LAS unsigned char* lds, const Sched& S, const Epi& E, const int wave_sgpr) {
;     ...
;         for (int t = 0; t < nt; t += 2) {
;     ...
;             PG8_LDA(At, 1, 1); PG8_STAGE(PG8_SB(1, 0), b3, voffB); PG8_STAGE(PG8_SB(1, 1), b3 + hstepB, voffB); PG8_STAGE(PG8_SA(1, 0), a3, voffA);
;             PG8_WAIT_V(8); PG8_WAIT_L(0); PG8_BAR; PG8_MMA(1, 0, At, B0); PG8_MMA(1, 1, At, B1); PG8_BAR; PG8_SCHED;
	s_add_i32 s20, s51, s26
	v_lshl_add_u64 v[142:143], v[142:143], 0, s[30:31]
	s_mov_b32 m0, s20
	ds_read_b128 v[180:183], v156 offset:49152
	ds_read_b128 v[184:187], v156 offset:50176
	ds_read_b128 v[188:191], v156 offset:51200
	ds_read_b128 v[192:195], v156 offset:52224
	ds_read_b128 v[196:199], v156 offset:53248
	ds_read_b128 v[200:203], v156 offset:54272
	ds_read_b128 v[204:207], v156 offset:55296
	ds_read_b128 v[208:211], v156 offset:56320
	global_load_lds_dwordx4 v[142:143], off
	s_add_i32 m0, s20, 0x2000
	s_add_u32 s18, s18, 0x80080
	v_lshl_add_u64 v[142:143], v[212:213], 0, s[30:31]
	s_addc_u32 s19, s19, 0
	s_add_i32 s20, s53, s26
	global_load_lds_dwordx4 v[142:143], off
	v_lshl_add_u64 v[142:143], s[18:19], 0, v[144:145]
	s_mov_b32 m0, s20
	s_nop 0
	global_load_lds_dwordx4 v[142:143], off
	v_lshl_add_u64 v[142:143], s[18:19], 0, v[128:129]
	s_add_i32 m0, s20, 0x2000
	s_nop 0
	global_load_lds_dwordx4 v[142:143], off
	v_lshl_add_u64 v[142:143], v[214:215], 0, s[30:31]
	s_mov_b32 m0, s38
	s_nop 0
	global_load_lds_dwordx4 v[142:143], off
	v_lshl_add_u64 v[142:143], v[216:217], 0, s[30:31]
	s_mov_b32 m0, s39
	s_nop 0
	global_load_lds_dwordx4 v[142:143], off
	s_waitcnt vmcnt(8)
	s_waitcnt lgkmcnt(0)
	s_barrier
	s_setprio 1
	s_waitcnt lgkmcnt(0)
	v_mfma_f32_16x16x32_bf16 v[60:63], v[138:141], v[180:183], v[60:63]
	v_mfma_f32_16x16x32_bf16 v[56:59], v[152:155], v[180:183], v[56:59]
	v_mfma_f32_16x16x32_bf16 v[44:47], v[138:141], v[188:191], v[44:47]
	v_mfma_f32_16x16x32_bf16 v[40:43], v[152:155], v[188:191], v[40:43]
	v_mfma_f32_16x16x32_bf16 v[28:31], v[138:141], v[196:199], v[28:31]
	v_mfma_f32_16x16x32_bf16 v[24:27], v[152:155], v[196:199], v[24:27]
	v_mfma_f32_16x16x32_bf16 v[12:15], v[138:141], v[204:207], v[12:15]
	v_mfma_f32_16x16x32_bf16 v[8:11], v[152:155], v[204:207], v[8:11]
	v_mfma_f32_16x16x32_bf16 v[60:63], v[148:151], v[184:187], v[60:63]
	v_mfma_f32_16x16x32_bf16 v[56:59], v[158:161], v[184:187], v[56:59]
	v_mfma_f32_16x16x32_bf16 v[44:47], v[148:151], v[192:195], v[44:47]
	v_mfma_f32_16x16x32_bf16 v[40:43], v[158:161], v[192:195], v[40:43]
	v_mfma_f32_16x16x32_bf16 v[28:31], v[148:151], v[200:203], v[28:31]
	v_mfma_f32_16x16x32_bf16 v[24:27], v[158:161], v[200:203], v[24:27]
	v_mfma_f32_16x16x32_bf16 v[12:15], v[148:151], v[208:211], v[12:15]
	v_mfma_f32_16x16x32_bf16 v[8:11], v[158:161], v[208:211], v[8:11]
	s_setprio 0
	s_setprio 1
	v_mfma_f32_16x16x32_bf16 v[52:55], v[162:165], v[180:183], v[52:55]
	v_mfma_f32_16x16x32_bf16 v[48:51], v[170:173], v[180:183], v[48:51]
	v_mfma_f32_16x16x32_bf16 v[36:39], v[162:165], v[188:191], v[36:39]
	v_mfma_f32_16x16x32_bf16 v[32:35], v[170:173], v[188:191], v[32:35]
	v_mfma_f32_16x16x32_bf16 v[20:23], v[162:165], v[196:199], v[20:23]
	v_mfma_f32_16x16x32_bf16 v[16:19], v[170:173], v[196:199], v[16:19]
	v_mfma_f32_16x16x32_bf16 v[4:7], v[162:165], v[204:207], v[4:7]
	v_mfma_f32_16x16x32_bf16 v[0:3], v[170:173], v[204:207], v[0:3]
	v_mfma_f32_16x16x32_bf16 v[52:55], v[166:169], v[184:187], v[52:55]
	v_mfma_f32_16x16x32_bf16 v[48:51], v[174:177], v[184:187], v[48:51]
	v_mfma_f32_16x16x32_bf16 v[36:39], v[166:169], v[192:195], v[36:39]
	v_mfma_f32_16x16x32_bf16 v[32:35], v[174:177], v[192:195], v[32:35]
	v_mfma_f32_16x16x32_bf16 v[20:23], v[166:169], v[200:203], v[20:23]
	v_mfma_f32_16x16x32_bf16 v[16:19], v[174:177], v[200:203], v[16:19]
	v_mfma_f32_16x16x32_bf16 v[4:7], v[166:169], v[208:211], v[4:7]
	v_mfma_f32_16x16x32_bf16 v[0:3], v[174:177], v[208:211], v[0:3]
	s_setprio 0
	s_add_i32 s50, s50, 2
	s_add_u32 s48, s48, 0x100
	s_addc_u32 s49, s49, 0
	s_add_u32 s16, s16, 0x100
	s_addc_u32 s17, s17, 0
	s_cmp_gt_u32 s50, 29
	s_barrier
	s_cbranch_scc0 .LBB0_1366
	s_and_b64 vcc, exec, s[6:7]
	s_cbranch_vccz .LBB0_1369
	s_barrier
